# P1 side task: 30 of 48 fragment loads issued before the first MFMA, counted vmcnt waits
# speedup vs baseline: 1.0026x; 1.0020x over previous
; #define LAS __attribute__((address_space(3)))
; __device__ __forceinline__ void p1_side_task(int c, LAS unsigned char* lds, const bf16_t* XN, const bf16_t* WIN, const float* b_f, float* LF, bf16_t* Kb, bf16_t* Vb, bf16_t* P1b) {
;     const int tid = threadIdx.x, lane = tid & 63, w = __builtin_amdgcn_readfirstlane(tid >> 6), fr = lane & 15, fq = lane >> 4;
;     const bf16_t* XM = XN + (size_t)MREAL * DM;
;     const bf16_t* WF = WIN + (size_t)20480 * DM;
;     int n0, n1;
;     if (c < 64) { n0 = 2048 + 32 * c; n1 = n0 + 16; } else if (c < 128) { n0 = 4096 + 32 * (c - 64); n1 = n0 + 16; }
;     else { const int ch0 = 16 * (c - 128); n0 = 8192 + 256 * (ch0 >> 7) + (ch0 & 127); n1 = n0 + 128; }
;     const size_t lo_ = (size_t)fr * DM + 256 * w + 8 * fq;
;     const bf16_t* P6[6] = {XN + (size_t)(32 * c) * DM + lo_, XN + (size_t)(32 * c + 16) * DM + lo_, XM + lo_, WF + lo_, WIN + (size_t)n0 * DM + lo_, WIN + (size_t)n1 * DM + lo_};
;     bf16x8 fr6[6][8];
; #pragma unroll
;     for (int s = 0; s < 6; ++s)
; #pragma unroll
;         for (int i = 0; i < 8; ++i) fr6[s][i] = *(const bf16x8*)(P6[s] + 32 * i);
;     f32x4 acc[5];
; #pragma unroll
;     for (int g = 0; g < 5; ++g) acc[g] = (f32x4){0.f, 0.f, 0.f, 0.f};
; #pragma unroll
;     for (int i = 0; i < 8; ++i) {
;         acc[0] = __builtin_amdgcn_mfma_f32_16x16x32_bf16(fr6[0][i], fr6[3][i], acc[0], 0, 0, 0);
;         acc[1] = __builtin_amdgcn_mfma_f32_16x16x32_bf16(fr6[1][i], fr6[3][i], acc[1], 0, 0, 0);
;         acc[2] = __builtin_amdgcn_mfma_f32_16x16x32_bf16(fr6[2][i], fr6[3][i], acc[2], 0, 0, 0);
;         acc[3] = __builtin_amdgcn_mfma_f32_16x16x32_bf16(fr6[4][i], fr6[2][i], acc[3], 0, 0, 0);
;         acc[4] = __builtin_amdgcn_mfma_f32_16x16x32_bf16(fr6[5][i], fr6[2][i], acc[4], 0, 0, 0);
;     }
;     LAS f32x4* red = (LAS f32x4*)lds;
; #pragma unroll
;     for (int g = 0; g < 5; ++g) red[(w * 5 + g) * 64 + lane] = acc[g];
;     __syncthreads();
.LBB0_423:
	s_ashr_i32 s11, s10, 31
	s_lshr_b32 s30, s37, 6
	s_lshl_b64 s[38:39], s[10:11], 12
	v_lshl_add_u32 v64, s30, 8, v90
	s_add_u32 s38, s4, s38
	v_lshlrev_b64 v[252:253], 1, v[64:65]
	s_addc_u32 s39, s5, s39
	v_lshl_add_u64 v[102:103], s[38:39], 0, v[252:253]
	s_add_i32 s40, s10, 16
	v_lshl_add_u64 v[98:99], s[2:3], 0, v[252:253]
	v_lshl_add_u64 v[100:101], s[8:9], 0, v[252:253]
	s_ashr_i32 s41, s40, 31
	s_lshl_b64 s[38:39], s[40:41], 12
	s_add_u32 s38, s4, s38
	s_addc_u32 s39, s5, s39
	v_lshl_add_u64 v[104:105], s[38:39], 0, v[252:253]
	global_load_dwordx4 v[24:27], v[102:103], off
	global_load_dwordx4 v[28:31], v[104:105], off
	global_load_dwordx4 v[32:35], v[98:99], off
	global_load_dwordx4 v[36:39], v[100:101], off
	v_readlane_b32 s40, v248, 29
	v_readlane_b32 s41, v248, 30
	v_readlane_b32 s42, v248, 31
	v_readlane_b32 s43, v248, 32
	v_readlane_b32 s44, v248, 33
	v_readlane_b32 s45, v248, 34
	s_ashr_i32 s29, s28, 31
	v_readlane_b32 s46, v248, 35
	v_readlane_b32 s47, v248, 36
	s_mov_b64 s[40:41], s[44:45]
	s_lshl_b64 s[28:29], s[28:29], 12
	s_mov_b64 s[42:43], s[46:47]
	s_add_u32 s28, s42, s28
	s_addc_u32 s29, s43, s29
	s_ashr_i32 s27, s26, 31
	s_lshl_b64 s[26:27], s[26:27], 12
	s_add_u32 s26, s42, s26
	s_addc_u32 s27, s43, s27
	v_lshl_add_u64 v[106:107], s[28:29], 0, v[252:253]
	v_lshl_add_u64 v[108:109], s[26:27], 0, v[252:253]
	global_load_dwordx4 v[40:43], v[106:107], off
	global_load_dwordx4 v[44:47], v[108:109], off
	global_load_dwordx4 v[48:51], v[102:103], off offset:64
	global_load_dwordx4 v[52:55], v[104:105], off offset:64
	global_load_dwordx4 v[56:59], v[98:99], off offset:64
	global_load_dwordx4 v[60:63], v[100:101], off offset:64
	global_load_dwordx4 v[82:85], v[106:107], off offset:64
	global_load_dwordx4 v[86:89], v[108:109], off offset:64
	global_load_dwordx4 v[162:165], v[102:103], off offset:128
	global_load_dwordx4 v[166:169], v[104:105], off offset:128
	global_load_dwordx4 v[170:173], v[98:99], off offset:128
	global_load_dwordx4 v[174:177], v[100:101], off offset:128
	global_load_dwordx4 v[178:181], v[106:107], off offset:128
	global_load_dwordx4 v[182:185], v[108:109], off offset:128
	global_load_dwordx4 v[188:191], v[102:103], off offset:192
	global_load_dwordx4 v[192:195], v[104:105], off offset:192
	global_load_dwordx4 v[196:199], v[98:99], off offset:192
	global_load_dwordx4 v[200:203], v[100:101], off offset:192
	global_load_dwordx4 v[204:207], v[106:107], off offset:192
	global_load_dwordx4 v[208:211], v[108:109], off offset:192
	global_load_dwordx4 v[212:215], v[102:103], off offset:256
	global_load_dwordx4 v[216:219], v[104:105], off offset:256
	global_load_dwordx4 v[220:223], v[98:99], off offset:256
	global_load_dwordx4 v[224:227], v[100:101], off offset:256
	global_load_dwordx4 v[228:231], v[106:107], off offset:256
	global_load_dwordx4 v[232:235], v[108:109], off offset:256
	s_mulk_i32 s30, 0x1400
	s_cmp_gt_u32 s37, 63
	v_add_u32_e32 v20, s30, v91
	s_waitcnt vmcnt(24)
	v_mfma_f32_16x16x32_bf16 v[0:3], v[24:27], v[36:39], 0
	v_mfma_f32_16x16x32_bf16 v[4:7], v[28:31], v[36:39], 0
	v_mfma_f32_16x16x32_bf16 v[8:11], v[32:35], v[36:39], 0
	v_mfma_f32_16x16x32_bf16 v[12:15], v[40:43], v[32:35], 0
	v_mfma_f32_16x16x32_bf16 v[16:19], v[44:47], v[32:35], 0
	s_nop 3
	global_load_dwordx4 v[24:27], v[102:103], off offset:320
	global_load_dwordx4 v[28:31], v[104:105], off offset:320
	global_load_dwordx4 v[32:35], v[98:99], off offset:320
	global_load_dwordx4 v[36:39], v[100:101], off offset:320
	global_load_dwordx4 v[40:43], v[106:107], off offset:320
	global_load_dwordx4 v[44:47], v[108:109], off offset:320
	s_waitcnt vmcnt(24)
	v_mfma_f32_16x16x32_bf16 v[0:3], v[48:51], v[60:63], v[0:3]
	v_mfma_f32_16x16x32_bf16 v[4:7], v[52:55], v[60:63], v[4:7]
	v_mfma_f32_16x16x32_bf16 v[8:11], v[56:59], v[60:63], v[8:11]
	v_mfma_f32_16x16x32_bf16 v[12:15], v[82:85], v[56:59], v[12:15]
	v_mfma_f32_16x16x32_bf16 v[16:19], v[86:89], v[56:59], v[16:19]
	s_nop 3
	global_load_dwordx4 v[48:51], v[102:103], off offset:384
	global_load_dwordx4 v[52:55], v[104:105], off offset:384
	global_load_dwordx4 v[56:59], v[98:99], off offset:384
	global_load_dwordx4 v[60:63], v[100:101], off offset:384
	global_load_dwordx4 v[82:85], v[106:107], off offset:384
	global_load_dwordx4 v[86:89], v[108:109], off offset:384
	s_waitcnt vmcnt(24)
	v_mfma_f32_16x16x32_bf16 v[0:3], v[162:165], v[174:177], v[0:3]
	v_mfma_f32_16x16x32_bf16 v[4:7], v[166:169], v[174:177], v[4:7]
	v_mfma_f32_16x16x32_bf16 v[8:11], v[170:173], v[174:177], v[8:11]
	v_mfma_f32_16x16x32_bf16 v[12:15], v[178:181], v[170:173], v[12:15]
	v_mfma_f32_16x16x32_bf16 v[16:19], v[182:185], v[170:173], v[16:19]
	s_nop 3
	global_load_dwordx4 v[162:165], v[102:103], off offset:448
	global_load_dwordx4 v[166:169], v[104:105], off offset:448
	global_load_dwordx4 v[170:173], v[98:99], off offset:448
	global_load_dwordx4 v[174:177], v[100:101], off offset:448
	global_load_dwordx4 v[178:181], v[106:107], off offset:448
	global_load_dwordx4 v[182:185], v[108:109], off offset:448
	s_waitcnt vmcnt(24)
	v_mfma_f32_16x16x32_bf16 v[0:3], v[188:191], v[200:203], v[0:3]
	v_mfma_f32_16x16x32_bf16 v[4:7], v[192:195], v[200:203], v[4:7]
	v_mfma_f32_16x16x32_bf16 v[8:11], v[196:199], v[200:203], v[8:11]
	v_mfma_f32_16x16x32_bf16 v[12:15], v[204:207], v[196:199], v[12:15]
	v_mfma_f32_16x16x32_bf16 v[16:19], v[208:211], v[196:199], v[16:19]
	s_waitcnt vmcnt(18)
	v_mfma_f32_16x16x32_bf16 v[0:3], v[212:215], v[224:227], v[0:3]
	v_mfma_f32_16x16x32_bf16 v[4:7], v[216:219], v[224:227], v[4:7]
	v_mfma_f32_16x16x32_bf16 v[8:11], v[220:223], v[224:227], v[8:11]
	v_mfma_f32_16x16x32_bf16 v[12:15], v[228:231], v[220:223], v[12:15]
	v_mfma_f32_16x16x32_bf16 v[16:19], v[232:235], v[220:223], v[16:19]
	s_waitcnt vmcnt(12)
	v_mfma_f32_16x16x32_bf16 v[0:3], v[24:27], v[36:39], v[0:3]
	v_mfma_f32_16x16x32_bf16 v[4:7], v[28:31], v[36:39], v[4:7]
	v_mfma_f32_16x16x32_bf16 v[8:11], v[32:35], v[36:39], v[8:11]
	v_mfma_f32_16x16x32_bf16 v[12:15], v[40:43], v[32:35], v[12:15]
	v_mfma_f32_16x16x32_bf16 v[16:19], v[44:47], v[32:35], v[16:19]
	s_waitcnt vmcnt(6)
	v_mfma_f32_16x16x32_bf16 v[0:3], v[48:51], v[60:63], v[0:3]
	v_mfma_f32_16x16x32_bf16 v[4:7], v[52:55], v[60:63], v[4:7]
	v_mfma_f32_16x16x32_bf16 v[8:11], v[56:59], v[60:63], v[8:11]
	v_mfma_f32_16x16x32_bf16 v[12:15], v[82:85], v[56:59], v[12:15]
	v_mfma_f32_16x16x32_bf16 v[16:19], v[86:89], v[56:59], v[16:19]
	s_waitcnt vmcnt(0)
	v_mfma_f32_16x16x32_bf16 v[0:3], v[162:165], v[174:177], v[0:3]
	v_mfma_f32_16x16x32_bf16 v[4:7], v[166:169], v[174:177], v[4:7]
	v_mfma_f32_16x16x32_bf16 v[8:11], v[170:173], v[174:177], v[8:11]
	v_mfma_f32_16x16x32_bf16 v[12:15], v[178:181], v[170:173], v[12:15]
	v_mfma_f32_16x16x32_bf16 v[16:19], v[182:185], v[170:173], v[16:19]
	s_nop 7
	s_nop 7
	s_nop 3
	ds_write_b128 v20, v[0:3]
	ds_write_b128 v20, v[4:7] offset:1024
	ds_write_b128 v20, v[8:11] offset:2048
	ds_write_b128 v20, v[12:15] offset:3072
	ds_write_b128 v20, v[16:19] offset:4096
	s_waitcnt lgkmcnt(0)
	s_barrier
; __device__ __forceinline__ void p1_side_task(int c, LAS unsigned char* lds, const bf16_t* XN, const bf16_t* WIN, const float* b_f, float* LF, bf16_t* Kb, bf16_t* Vb, bf16_t* P1b) {
;     ...
;     if (w == 0) {
; #pragma unroll
;         for (int g = 0; g < 5; ++g) { f32x4 s = red[g * 64 + lane];
; #pragma unroll
;             for (int ww = 1; ww < 8; ++ww) s += red[(ww * 5 + g) * 64 + lane];
;             acc[g] = s; }
;         const float bfh = b_f[fr];
; #pragma unroll
;         for (int g = 0; g < 3; ++g)
; #pragma unroll
;             for (int j = 0; j < 4; ++j) { const float xx = acc[g][j] + bfh; const float v = (fminf(xx, 0.f) - log1pf(__expf(-fabsf(xx)))) * LOG2E; const int m = 4 * fq + j;
;                 if (g < 2) { const int row = 32 * c + 16 * g + m; LF[(size_t)((row >> 12) * NH + fr) * KVROWS + 64 + (row & 4095)] = v; }
	s_cbranch_scc1 .LBB0_414
	global_load_dword v97, v[66:67], off
	ds_read_b128 v[82:85], v91
	ds_read_b128 v[98:101], v91 offset:1024
	ds_read_b128 v[102:105], v91 offset:5120
	ds_read_b128 v[106:109], v91 offset:6144
	ds_read_b128 v[110:113], v91 offset:10240
	ds_read_b128 v[114:117], v91 offset:11264
	ds_read_b128 v[118:121], v91 offset:15360
	ds_read_b128 v[122:125], v91 offset:16384
	ds_read_b128 v[126:129], v91 offset:20480
	ds_read_b128 v[130:133], v91 offset:21504
	ds_read_b128 v[138:141], v91 offset:25600
	ds_read_b128 v[142:145], v91 offset:26624
	ds_read_b128 v[146:149], v91 offset:30720
	ds_read_b128 v[150:153], v91 offset:31744
	ds_read_b128 v[154:157], v91 offset:35840
	ds_read_b128 v[158:161], v91 offset:36864
	ds_read_b128 v[52:55], v91 offset:3072
	ds_read_b128 v[20:23], v91 offset:4096
	ds_read_b128 v[60:63], v91 offset:8192
	ds_read_b128 v[28:31], v91 offset:9216
	ds_read_b128 v[56:59], v91 offset:13312
	ds_read_b128 v[24:27], v91 offset:14336
	ds_read_b128 v[48:51], v91 offset:18432
	ds_read_b128 v[16:19], v91 offset:19456
	ds_read_b128 v[44:47], v91 offset:23552
	ds_read_b128 v[12:15], v91 offset:24576
	ds_read_b128 v[40:43], v91 offset:28672
	ds_read_b128 v[8:11], v91 offset:29696
	ds_read_b128 v[36:39], v91 offset:33792
	ds_read_b128 v[4:7], v91 offset:34816
	ds_read_b128 v[32:35], v91 offset:38912
	ds_read_b128 v[0:3], v91 offset:39936
	s_waitcnt lgkmcnt(14)
	v_pk_add_f32 v[84:85], v[84:85], v[104:105]
	v_pk_add_f32 v[82:83], v[82:83], v[102:103]
	v_pk_add_f32 v[84:85], v[84:85], v[112:113]
	v_pk_add_f32 v[82:83], v[82:83], v[110:111]
	v_pk_add_f32 v[88:89], v[100:101], v[108:109]
	v_pk_add_f32 v[98:99], v[98:99], v[106:107]
	v_pk_add_f32 v[84:85], v[84:85], v[120:121]
	v_pk_add_f32 v[82:83], v[82:83], v[118:119]
	v_pk_add_f32 v[88:89], v[88:89], v[116:117]
	v_pk_add_f32 v[98:99], v[98:99], v[114:115]
	v_pk_add_f32 v[84:85], v[84:85], v[128:129]
	v_pk_add_f32 v[82:83], v[82:83], v[126:127]
	v_pk_add_f32 v[88:89], v[88:89], v[124:125]
	v_pk_add_f32 v[98:99], v[98:99], v[122:123]
	v_pk_add_f32 v[84:85], v[84:85], v[140:141]
	v_pk_add_f32 v[82:83], v[82:83], v[138:139]
	v_pk_add_f32 v[88:89], v[88:89], v[132:133]
	v_pk_add_f32 v[98:99], v[98:99], v[130:131]
	v_pk_add_f32 v[84:85], v[84:85], v[148:149]
	v_pk_add_f32 v[82:83], v[82:83], v[146:147]
	v_pk_add_f32 v[88:89], v[88:89], v[144:145]
	v_pk_add_f32 v[98:99], v[98:99], v[142:143]
	v_pk_add_f32 v[100:101], v[84:85], v[156:157]
	v_pk_add_f32 v[84:85], v[82:83], v[154:155]
	v_pk_add_f32 v[88:89], v[88:89], v[152:153]
	v_pk_add_f32 v[98:99], v[98:99], v[150:151]
	v_pk_add_f32 v[82:83], v[88:89], v[160:161]
	v_pk_add_f32 v[88:89], v[98:99], v[158:159]
	s_lshr_b32 s11, s10, 8
	s_and_b32 s26, s10, 0xfe0
	s_and_b32 s11, s11, 0xfffff0
	v_or_b32_e32 v64, s26, v92
	v_or_b32_e32 v86, s11, v136
	v_readlane_b32 s26, v248, 52
	v_mul_hi_i32_i24_e32 v87, 0x4100, v86
	v_mul_i32_i24_e32 v86, 0x4100, v86
	v_readlane_b32 s27, v248, 53
	v_lshlrev_b32_e32 v64, 2, v64
	s_cmp_lg_u32 s36, 0
	v_lshl_add_u64 v[86:87], s[26:27], 0, v[86:87]
	v_lshl_add_u64 v[86:87], v[86:87], 0, v[64:65]
	s_waitcnt vmcnt(0)
	v_add_f32_e32 v84, v84, v97
	v_add_f32_e32 v85, v85, v97
	v_mul_f32_e64 v98, |v84|, s19
	v_mul_f32_e64 v99, |v85|, s19
	v_exp_f32_e32 v130, v98
	v_exp_f32_e32 v131, v99
	v_min_f32_e32 v98, 0, v84
	v_min_f32_e32 v99, 0, v85
	v_add_f32_e32 v104, 1.0, v130
	v_add_f32_e32 v106, 1.0, v131
	v_cvt_f64_f32_e32 v[84:85], v104
	v_add_f32_e32 v107, -1.0, v104
	v_cvt_f64_f32_e32 v[102:103], v106
	v_frexp_exp_i32_f64_e32 v84, v[84:85]
	v_sub_f32_e32 v85, v130, v107
	v_sub_f32_e32 v107, v107, v104
	v_frexp_exp_i32_f64_e32 v102, v[102:103]
	v_add_f32_e32 v103, 1.0, v107
	v_add_f32_e32 v85, v85, v103
	v_add_f32_e32 v103, -1.0, v106
	v_frexp_mant_f32_e32 v108, v106
	v_sub_f32_e32 v107, v131, v103
	v_sub_f32_e32 v103, v103, v106
	v_add_f32_e32 v103, 1.0, v103
	v_cmp_gt_f32_e32 vcc, s21, v108
	v_frexp_mant_f32_e32 v105, v104
	v_add_f32_e32 v103, v107, v103
	v_subbrev_co_u32_e32 v107, vcc, 0, v102, vcc
	v_cmp_gt_f32_e32 vcc, s21, v105
	v_cvt_f32_i32_e32 v105, v107
	v_sub_u32_e32 v107, 0, v107
	v_subbrev_co_u32_e32 v108, vcc, 0, v84, vcc
	v_sub_u32_e32 v102, 0, v108
	v_ldexp_f32 v84, v104, v102
	v_ldexp_f32 v102, v85, v102
	v_ldexp_f32 v85, v106, v107
	v_pk_add_f32 v[116:117], v[84:85], 1.0 op_sel_hi:[1,0]
	v_ldexp_f32 v103, v103, v107
	v_pk_add_f32 v[118:119], v[116:117], -1.0 op_sel_hi:[1,0]
	v_pk_add_f32 v[112:113], v[84:85], -1.0 op_sel_hi:[1,0]
	v_pk_add_f32 v[118:119], v[84:85], v[118:119] neg_lo:[0,1] neg_hi:[0,1]
	v_pk_add_f32 v[114:115], v[112:113], 1.0 op_sel_hi:[1,0]
	v_pk_add_f32 v[118:119], v[102:103], v[118:119]
	v_pk_add_f32 v[84:85], v[84:85], v[114:115] neg_lo:[0,1] neg_hi:[0,1]
	v_pk_add_f32 v[120:121], v[116:117], v[118:119]
	v_pk_add_f32 v[84:85], v[102:103], v[84:85]
	v_rcp_f32_e32 v122, v120
	v_rcp_f32_e32 v123, v121
	v_pk_add_f32 v[102:103], v[112:113], v[84:85]
	v_pk_add_f32 v[116:117], v[120:121], v[116:117] neg_lo:[0,1] neg_hi:[0,1]
	v_pk_add_f32 v[112:113], v[102:103], v[112:113] neg_lo:[0,1] neg_hi:[0,1]
	v_pk_mul_f32 v[114:115], v[102:103], v[122:123]
	v_pk_add_f32 v[116:117], v[118:119], v[116:117] neg_lo:[0,1] neg_hi:[0,1]
	v_pk_mul_f32 v[124:125], v[120:121], v[114:115]
	v_pk_add_f32 v[84:85], v[84:85], v[112:113] neg_lo:[0,1] neg_hi:[0,1]
	v_pk_fma_f32 v[118:119], v[114:115], v[120:121], v[124:125] neg_lo:[0,0,1] neg_hi:[0,0,1]
	v_cvt_f32_i32_e32 v104, v108
	v_pk_fma_f32 v[118:119], v[114:115], v[116:117], v[118:119]
	v_cmp_neq_f32_e32 vcc, s33, v130
	v_pk_add_f32 v[126:127], v[124:125], v[118:119]
	v_pk_mul_f32 v[106:107], v[104:105], s[12:13] op_sel_hi:[1,0]
; __device__ __forceinline__ void p1_side_task(int c, LAS unsigned char* lds, const bf16_t* XN, const bf16_t* WIN, const float* b_f, float* LF, bf16_t* Kb, bf16_t* Vb, bf16_t* P1b) {
;     ...
;             for (int j = 0; j < 4; ++j) { const float xx = acc[g][j] + bfh; const float v = (fminf(xx, 0.f) - log1pf(__expf(-fabsf(xx)))) * LOG2E; const int m = 4 * fq + j;
;                 if (g < 2) { const int row = 32 * c + 16 * g + m; LF[(size_t)((row >> 12) * NH + fr) * KVROWS + 64 + (row & 4095)] = v; }
	v_pk_add_f32 v[128:129], v[102:103], v[126:127] neg_lo:[0,1] neg_hi:[0,1]
	v_pk_add_f32 v[124:125], v[126:127], v[124:125] neg_lo:[0,1] neg_hi:[0,1]
	v_pk_add_f32 v[102:103], v[102:103], v[128:129] neg_lo:[0,1] neg_hi:[0,1]
	v_pk_add_f32 v[118:119], v[124:125], v[118:119] neg_lo:[0,1] neg_hi:[0,1]
	v_pk_add_f32 v[102:103], v[102:103], v[126:127] neg_lo:[0,1] neg_hi:[0,1]
	v_pk_fma_f32 v[108:109], v[104:105], s[12:13], v[106:107] op_sel_hi:[1,0,1] neg_lo:[0,0,1] neg_hi:[0,0,1]
	v_pk_add_f32 v[84:85], v[84:85], v[102:103]
	v_pk_fma_f32 v[104:105], v[104:105], s[14:15], v[108:109] op_sel_hi:[1,0,1]
	v_pk_add_f32 v[84:85], v[118:119], v[84:85]
	v_pk_add_f32 v[108:109], v[106:107], v[104:105]
	v_pk_add_f32 v[102:103], v[128:129], v[84:85]
	v_pk_add_f32 v[110:111], v[108:109], v[106:107] neg_lo:[0,1] neg_hi:[0,1]
	v_pk_mul_f32 v[112:113], v[122:123], v[102:103]
	v_mov_b32_e32 v106, v108
	v_pk_mul_f32 v[118:119], v[120:121], v[112:113]
	v_pk_add_f32 v[124:125], v[114:115], v[112:113]
	v_pk_fma_f32 v[120:121], v[112:113], v[120:121], v[118:119] neg_lo:[0,0,1] neg_hi:[0,0,1]
	v_pk_add_f32 v[114:115], v[124:125], v[114:115] neg_lo:[0,1] neg_hi:[0,1]
	v_add_f32_e32 v100, v100, v97
	v_pk_add_f32 v[114:115], v[112:113], v[114:115] neg_lo:[0,1] neg_hi:[0,1]
	v_pk_fma_f32 v[112:113], v[112:113], v[116:117], v[120:121]
	v_add_f32_e32 v101, v101, v97
	v_pk_add_f32 v[116:117], v[118:119], v[112:113]
	v_add_f32_e32 v89, v89, v97
	v_pk_add_f32 v[120:121], v[102:103], v[116:117] neg_lo:[0,1] neg_hi:[0,1]
	v_pk_add_f32 v[118:119], v[116:117], v[118:119] neg_lo:[0,1] neg_hi:[0,1]
	v_add_f32_e32 v83, v83, v97
	v_pk_add_f32 v[112:113], v[118:119], v[112:113] neg_lo:[0,1] neg_hi:[0,1]
	v_pk_add_f32 v[118:119], v[128:129], v[102:103] neg_lo:[0,1] neg_hi:[0,1]
	v_pk_add_f32 v[102:103], v[102:103], v[120:121] neg_lo:[0,1] neg_hi:[0,1]
	v_pk_add_f32 v[84:85], v[84:85], v[118:119]
	v_pk_add_f32 v[102:103], v[102:103], v[116:117] neg_lo:[0,1] neg_hi:[0,1]
	s_nop 0
	v_pk_add_f32 v[84:85], v[84:85], v[102:103]
	s_nop 0
	v_pk_add_f32 v[84:85], v[112:113], v[84:85]
	s_nop 0
	v_pk_add_f32 v[84:85], v[120:121], v[84:85]
	v_mov_b32_e32 v121, v109
	v_pk_mul_f32 v[84:85], v[122:123], v[84:85]
	s_nop 0
	v_pk_add_f32 v[84:85], v[114:115], v[84:85]
	s_nop 0
	v_pk_add_f32 v[102:103], v[124:125], v[84:85]
	s_nop 0
	v_pk_add_f32 v[114:115], v[102:103], v[124:125] neg_lo:[0,1] neg_hi:[0,1]
	v_pk_mul_f32 v[116:117], v[102:103], v[102:103]
	v_pk_add_f32 v[114:115], v[84:85], v[114:115] neg_lo:[0,1] neg_hi:[0,1]
	v_mov_b64_e32 v[84:85], s[16:17]
	v_pk_fma_f32 v[118:119], v[116:117], s[18:19], v[84:85] op_sel_hi:[1,0,0]
	v_ldexp_f32 v112, v102, 1
	v_ldexp_f32 v113, v103, 1
	v_pk_mul_f32 v[102:103], v[102:103], v[116:117]
	v_pk_fma_f32 v[116:117], v[116:117], v[118:119], s[20:21] op_sel_hi:[1,1,0]
	v_ldexp_f32 v114, v114, 1
	v_pk_mul_f32 v[102:103], v[102:103], v[116:117]
	v_ldexp_f32 v115, v115, 1
	v_pk_add_f32 v[116:117], v[112:113], v[102:103]
	s_nop 0
	v_pk_add_f32 v[112:113], v[116:117], v[112:113] neg_lo:[0,1] neg_hi:[0,1]
	s_nop 0
	v_pk_add_f32 v[102:103], v[102:103], v[112:113] neg_lo:[0,1] neg_hi:[0,1]
	s_nop 0
	v_pk_add_f32 v[102:103], v[114:115], v[102:103]
	s_nop 0
	v_pk_add_f32 v[112:113], v[116:117], v[102:103]
	s_nop 0
	v_pk_add_f32 v[118:119], v[108:109], v[112:113]
	v_pk_add_f32 v[114:115], v[112:113], v[116:117] neg_lo:[0,1] neg_hi:[0,1]
	v_mov_b32_e32 v120, v118
	v_pk_add_f32 v[106:107], v[120:121], v[106:107] neg_lo:[0,1] neg_hi:[0,1]
	v_mov_b32_e32 v120, v112
	v_mov_b32_e32 v121, v105
	v_pk_add_f32 v[120:121], v[120:121], v[106:107] neg_lo:[0,1] neg_hi:[0,1]
	v_mov_b32_e32 v111, v107
	v_mov_b32_e32 v112, v118
	v_mov_b32_e32 v107, v117
	v_pk_add_f32 v[106:107], v[112:113], v[106:107] neg_lo:[0,1] neg_hi:[0,1]
	v_mov_b32_e32 v116, v108
	v_mov_b32_e32 v117, v103
	v_mov_b32_e32 v115, v107
	v_pk_add_f32 v[124:125], v[118:119], v[108:109] neg_lo:[0,1] neg_hi:[0,1]
	v_pk_add_f32 v[116:117], v[116:117], v[106:107] neg_lo:[0,1] neg_hi:[0,1]
	v_pk_add_f32 v[106:107], v[102:103], v[114:115] neg_lo:[0,1] neg_hi:[0,1]
	v_mov_b32_e32 v103, v113
	v_pk_add_f32 v[112:113], v[118:119], v[124:125] neg_lo:[0,1] neg_hi:[0,1]
	v_pk_add_f32 v[122:123], v[104:105], v[110:111] neg_lo:[0,1] neg_hi:[0,1]
	v_mov_b32_e32 v115, v125
	v_mov_b32_e32 v105, v109
	v_mov_b32_e32 v111, v113
	v_pk_add_f32 v[102:103], v[102:103], v[114:115] neg_lo:[0,1] neg_hi:[0,1]
	v_pk_add_f32 v[104:105], v[104:105], v[110:111] neg_lo:[0,1] neg_hi:[0,1]
	v_pk_add_f32 v[116:117], v[120:121], v[116:117]
	v_pk_add_f32 v[102:103], v[102:103], v[104:105]
	v_mov_b32_e32 v105, v121
	v_pk_add_f32 v[108:109], v[116:117], v[102:103]
	v_mov_b32_e32 v103, v117
	v_pk_add_f32 v[104:105], v[102:103], v[104:105] neg_lo:[0,1] neg_hi:[0,1]
	v_pk_add_f32 v[110:111], v[118:119], v[108:109]
	v_pk_add_f32 v[102:103], v[102:103], v[104:105] neg_lo:[0,1] neg_hi:[0,1]
	v_pk_add_f32 v[106:107], v[106:107], v[104:105] neg_lo:[0,1] neg_hi:[0,1]
	v_pk_add_f32 v[102:103], v[122:123], v[102:103] neg_lo:[0,1] neg_hi:[0,1]
	v_pk_add_f32 v[104:105], v[110:111], v[118:119] neg_lo:[0,1] neg_hi:[0,1]
	v_pk_add_f32 v[102:103], v[106:107], v[102:103]
	v_pk_add_f32 v[104:105], v[108:109], v[104:105] neg_lo:[0,1] neg_hi:[0,1]
	s_nop 0
	v_pk_add_f32 v[102:103], v[102:103], v[104:105]
	v_mul_f32_e64 v104, |v100|, s19
	v_pk_add_f32 v[102:103], v[110:111], v[102:103]
	v_exp_f32_e32 v132, v104
	v_cndmask_b32_e32 v102, v94, v102, vcc
	v_cmp_neq_f32_e32 vcc, s33, v131
	v_min_f32_e32 v100, 0, v100
	v_add_f32_e32 v104, 1.0, v132
	v_cndmask_b32_e32 v103, v94, v103, vcc
	v_cmp_ngt_f32_e32 vcc, -1.0, v131
	v_frexp_mant_f32_e32 v106, v104
	s_nop 0
	v_cndmask_b32_e32 v103, v95, v103, vcc
; __device__ __forceinline__ void p1_side_task(int c, LAS unsigned char* lds, const bf16_t* XN, const bf16_t* WIN, const float* b_f, float* LF, bf16_t* Kb, bf16_t* Vb, bf16_t* P1b) {
;     ...
;             for (int j = 0; j < 4; ++j) { const float xx = acc[g][j] + bfh; const float v = (fminf(xx, 0.f) - log1pf(__expf(-fabsf(xx)))) * LOG2E; const int m = 4 * fq + j;
;                 if (g < 2) { const int row = 32 * c + 16 * g + m; LF[(size_t)((row >> 12) * NH + fr) * KVROWS + 64 + (row & 4095)] = v; }
	v_cmp_ngt_f32_e32 vcc, -1.0, v130
	s_nop 1
	v_cndmask_b32_e32 v102, v95, v102, vcc
	v_cmp_neq_f32_e32 vcc, -1.0, v130
	s_nop 1
	v_cndmask_b32_e32 v102, v96, v102, vcc
	v_cmp_neq_f32_e32 vcc, -1.0, v131
	s_nop 1
	v_cndmask_b32_e32 v103, v96, v103, vcc
	v_cmp_lt_f32_e64 vcc, |v131|, s23
	s_nop 1
	v_cndmask_b32_e32 v103, v103, v131, vcc
	v_cmp_lt_f32_e64 vcc, |v130|, s23
	s_nop 1
	v_cndmask_b32_e32 v102, v102, v130, vcc
	v_pk_add_f32 v[98:99], v[98:99], v[102:103] neg_lo:[0,1] neg_hi:[0,1]
	v_cvt_f64_f32_e32 v[102:103], v104
	v_frexp_exp_i32_f64_e32 v105, v[102:103]
	v_add_f32_e32 v102, -1.0, v104
	v_sub_f32_e32 v103, v132, v102
	v_sub_f32_e32 v102, v102, v104
	v_add_f32_e32 v102, 1.0, v102
	v_add_f32_e32 v107, v103, v102
	v_mul_f32_e64 v102, |v101|, s19
	v_exp_f32_e32 v133, v102
	v_min_f32_e32 v101, 0, v101
	v_pk_mul_f32 v[98:99], v[98:99], s[22:23] op_sel_hi:[1,0]
	v_add_f32_e32 v64, 1.0, v133
	v_cvt_f64_f32_e32 v[102:103], v64
	v_frexp_exp_i32_f64_e32 v102, v[102:103]
	v_frexp_mant_f32_e32 v103, v64
	v_cmp_gt_f32_e32 vcc, s21, v103
	v_add_f32_e32 v108, -1.0, v64
	v_sub_f32_e32 v109, v133, v108
	v_subbrev_co_u32_e32 v103, vcc, 0, v102, vcc
	v_cmp_gt_f32_e32 vcc, s21, v106
	v_sub_f32_e32 v108, v108, v64
	v_add_f32_e32 v108, 1.0, v108
	v_subbrev_co_u32_e32 v105, vcc, 0, v105, vcc
	v_sub_u32_e32 v106, 0, v105
	v_ldexp_f32 v102, v104, v106
	v_ldexp_f32 v104, v107, v106
	v_cvt_f32_i32_e32 v106, v105
	v_sub_u32_e32 v105, 0, v103
	v_cvt_f32_i32_e32 v107, v103
	v_ldexp_f32 v103, v64, v105
	v_pk_add_f32 v[118:119], v[102:103], 1.0 op_sel_hi:[1,0]
	v_add_f32_e32 v108, v109, v108
	v_pk_add_f32 v[120:121], v[118:119], -1.0 op_sel_hi:[1,0]
	v_ldexp_f32 v105, v108, v105
	v_pk_add_f32 v[120:121], v[102:103], v[120:121] neg_lo:[0,1] neg_hi:[0,1]
	v_pk_add_f32 v[114:115], v[102:103], -1.0 op_sel_hi:[1,0]
	v_pk_add_f32 v[120:121], v[104:105], v[120:121]
	v_pk_add_f32 v[116:117], v[114:115], 1.0 op_sel_hi:[1,0]
	v_pk_add_f32 v[122:123], v[118:119], v[120:121]
	v_pk_add_f32 v[102:103], v[102:103], v[116:117] neg_lo:[0,1] neg_hi:[0,1]
	v_rcp_f32_e32 v124, v122
	v_rcp_f32_e32 v125, v123
	v_pk_add_f32 v[102:103], v[104:105], v[102:103]
	v_pk_add_f32 v[118:119], v[122:123], v[118:119] neg_lo:[0,1] neg_hi:[0,1]
	v_pk_add_f32 v[104:105], v[114:115], v[102:103]
	v_pk_add_f32 v[118:119], v[120:121], v[118:119] neg_lo:[0,1] neg_hi:[0,1]
	v_pk_mul_f32 v[116:117], v[104:105], v[124:125]
	v_pk_add_f32 v[114:115], v[104:105], v[114:115] neg_lo:[0,1] neg_hi:[0,1]
	v_pk_mul_f32 v[126:127], v[122:123], v[116:117]
	v_pk_add_f32 v[102:103], v[102:103], v[114:115] neg_lo:[0,1] neg_hi:[0,1]
	v_pk_fma_f32 v[120:121], v[116:117], v[122:123], v[126:127] neg_lo:[0,0,1] neg_hi:[0,0,1]
	v_pk_mul_f32 v[108:109], v[106:107], s[12:13] op_sel_hi:[1,0]
	v_pk_fma_f32 v[120:121], v[116:117], v[118:119], v[120:121]
	v_pk_fma_f32 v[110:111], v[106:107], s[12:13], v[108:109] op_sel_hi:[1,0,1] neg_lo:[0,0,1] neg_hi:[0,0,1]
	v_pk_add_f32 v[128:129], v[126:127], v[120:121]
	v_pk_fma_f32 v[106:107], v[106:107], s[14:15], v[110:111] op_sel_hi:[1,0,1]
	v_pk_add_f32 v[130:131], v[104:105], v[128:129] neg_lo:[0,1] neg_hi:[0,1]
	v_pk_add_f32 v[126:127], v[128:129], v[126:127] neg_lo:[0,1] neg_hi:[0,1]
	v_pk_add_f32 v[104:105], v[104:105], v[130:131] neg_lo:[0,1] neg_hi:[0,1]
	v_pk_add_f32 v[120:121], v[126:127], v[120:121] neg_lo:[0,1] neg_hi:[0,1]
	v_pk_add_f32 v[104:105], v[104:105], v[128:129] neg_lo:[0,1] neg_hi:[0,1]
	v_pk_add_f32 v[110:111], v[108:109], v[106:107]
	v_pk_add_f32 v[102:103], v[102:103], v[104:105]
	v_pk_add_f32 v[112:113], v[110:111], v[108:109] neg_lo:[0,1] neg_hi:[0,1]
	v_pk_add_f32 v[102:103], v[120:121], v[102:103]
	v_mov_b32_e32 v108, v110
	v_pk_add_f32 v[104:105], v[130:131], v[102:103]
	v_cmp_neq_f32_e32 vcc, s33, v132
	v_pk_mul_f32 v[114:115], v[124:125], v[104:105]
	s_nop 0
	v_pk_mul_f32 v[120:121], v[122:123], v[114:115]
	v_pk_add_f32 v[126:127], v[116:117], v[114:115]
	v_pk_fma_f32 v[122:123], v[114:115], v[122:123], v[120:121] neg_lo:[0,0,1] neg_hi:[0,0,1]
	v_pk_add_f32 v[116:117], v[126:127], v[116:117] neg_lo:[0,1] neg_hi:[0,1]
	s_nop 0
	v_pk_add_f32 v[116:117], v[114:115], v[116:117] neg_lo:[0,1] neg_hi:[0,1]
	v_pk_fma_f32 v[114:115], v[114:115], v[118:119], v[122:123]
	s_nop 0
	v_pk_add_f32 v[118:119], v[120:121], v[114:115]
	s_nop 0
	v_pk_add_f32 v[122:123], v[104:105], v[118:119] neg_lo:[0,1] neg_hi:[0,1]
	v_pk_add_f32 v[120:121], v[118:119], v[120:121] neg_lo:[0,1] neg_hi:[0,1]
	s_nop 0
	v_pk_add_f32 v[114:115], v[120:121], v[114:115] neg_lo:[0,1] neg_hi:[0,1]
	v_pk_add_f32 v[120:121], v[130:131], v[104:105] neg_lo:[0,1] neg_hi:[0,1]
	v_pk_add_f32 v[104:105], v[104:105], v[122:123] neg_lo:[0,1] neg_hi:[0,1]
	v_pk_add_f32 v[102:103], v[102:103], v[120:121]
	v_pk_add_f32 v[104:105], v[104:105], v[118:119] neg_lo:[0,1] neg_hi:[0,1]
	v_mov_b32_e32 v121, v111
	v_pk_add_f32 v[102:103], v[102:103], v[104:105]
	s_nop 0
	v_pk_add_f32 v[102:103], v[114:115], v[102:103]
	s_nop 0
	v_pk_add_f32 v[102:103], v[122:123], v[102:103]
	s_nop 0
	v_pk_mul_f32 v[102:103], v[124:125], v[102:103]
	s_nop 0
	v_pk_add_f32 v[102:103], v[116:117], v[102:103]
	s_nop 0
	v_pk_add_f32 v[104:105], v[126:127], v[102:103]
	s_nop 0
	v_pk_add_f32 v[116:117], v[104:105], v[126:127] neg_lo:[0,1] neg_hi:[0,1]
	v_ldexp_f32 v114, v104, 1
	v_pk_add_f32 v[102:103], v[102:103], v[116:117] neg_lo:[0,1] neg_hi:[0,1]
	v_pk_mul_f32 v[116:117], v[104:105], v[104:105]
	v_ldexp_f32 v115, v105, 1
	v_pk_fma_f32 v[118:119], v[116:117], s[18:19], v[84:85] op_sel_hi:[1,0,0]
	v_pk_mul_f32 v[104:105], v[104:105], v[116:117]
	v_pk_fma_f32 v[116:117], v[116:117], v[118:119], s[20:21] op_sel_hi:[1,1,0]
	v_ldexp_f32 v102, v102, 1
; __device__ __forceinline__ void p1_side_task(int c, LAS unsigned char* lds, const bf16_t* XN, const bf16_t* WIN, const float* b_f, float* LF, bf16_t* Kb, bf16_t* Vb, bf16_t* P1b) {
;     ...
;             for (int j = 0; j < 4; ++j) { const float xx = acc[g][j] + bfh; const float v = (fminf(xx, 0.f) - log1pf(__expf(-fabsf(xx)))) * LOG2E; const int m = 4 * fq + j;
;                 if (g < 2) { const int row = 32 * c + 16 * g + m; LF[(size_t)((row >> 12) * NH + fr) * KVROWS + 64 + (row & 4095)] = v; }
	v_pk_mul_f32 v[104:105], v[104:105], v[116:117]
	v_ldexp_f32 v103, v103, 1
	v_pk_add_f32 v[116:117], v[114:115], v[104:105]
	s_nop 0
	v_pk_add_f32 v[114:115], v[116:117], v[114:115] neg_lo:[0,1] neg_hi:[0,1]
	s_nop 0
	v_pk_add_f32 v[104:105], v[104:105], v[114:115] neg_lo:[0,1] neg_hi:[0,1]
	s_nop 0
	v_pk_add_f32 v[102:103], v[102:103], v[104:105]
	s_nop 0
	v_pk_add_f32 v[104:105], v[116:117], v[102:103]
	s_nop 0
	v_pk_add_f32 v[118:119], v[110:111], v[104:105]
	v_pk_add_f32 v[114:115], v[104:105], v[116:117] neg_lo:[0,1] neg_hi:[0,1]
	v_mov_b32_e32 v120, v118
	v_pk_add_f32 v[108:109], v[120:121], v[108:109] neg_lo:[0,1] neg_hi:[0,1]
	v_mov_b32_e32 v120, v104
	v_mov_b32_e32 v121, v107
	v_pk_add_f32 v[120:121], v[120:121], v[108:109] neg_lo:[0,1] neg_hi:[0,1]
	v_mov_b32_e32 v113, v109
	v_mov_b32_e32 v104, v118
	v_mov_b32_e32 v109, v117
	v_pk_add_f32 v[108:109], v[104:105], v[108:109] neg_lo:[0,1] neg_hi:[0,1]
	v_mov_b32_e32 v116, v110
	v_mov_b32_e32 v117, v103
	v_mov_b32_e32 v115, v109
	v_pk_add_f32 v[124:125], v[118:119], v[110:111] neg_lo:[0,1] neg_hi:[0,1]
	v_pk_add_f32 v[116:117], v[116:117], v[108:109] neg_lo:[0,1] neg_hi:[0,1]
	v_pk_add_f32 v[108:109], v[102:103], v[114:115] neg_lo:[0,1] neg_hi:[0,1]
	v_mov_b32_e32 v103, v105
	v_pk_add_f32 v[104:105], v[118:119], v[124:125] neg_lo:[0,1] neg_hi:[0,1]
	v_pk_add_f32 v[122:123], v[106:107], v[112:113] neg_lo:[0,1] neg_hi:[0,1]
	v_mov_b32_e32 v115, v125
	v_mov_b32_e32 v107, v111
	v_mov_b32_e32 v113, v105
	v_pk_add_f32 v[102:103], v[102:103], v[114:115] neg_lo:[0,1] neg_hi:[0,1]
	v_pk_add_f32 v[104:105], v[106:107], v[112:113] neg_lo:[0,1] neg_hi:[0,1]
	v_pk_add_f32 v[116:117], v[120:121], v[116:117]
	v_pk_add_f32 v[102:103], v[102:103], v[104:105]
	v_mov_b32_e32 v105, v121
	v_pk_add_f32 v[106:107], v[116:117], v[102:103]
	v_mov_b32_e32 v103, v117
	v_pk_add_f32 v[104:105], v[102:103], v[104:105] neg_lo:[0,1] neg_hi:[0,1]
	v_pk_add_f32 v[110:111], v[118:119], v[106:107]
	v_pk_add_f32 v[102:103], v[102:103], v[104:105] neg_lo:[0,1] neg_hi:[0,1]
	v_pk_add_f32 v[108:109], v[108:109], v[104:105] neg_lo:[0,1] neg_hi:[0,1]
	v_pk_add_f32 v[102:103], v[122:123], v[102:103] neg_lo:[0,1] neg_hi:[0,1]
	v_pk_add_f32 v[104:105], v[110:111], v[118:119] neg_lo:[0,1] neg_hi:[0,1]
	v_pk_add_f32 v[102:103], v[108:109], v[102:103]
	v_pk_add_f32 v[104:105], v[106:107], v[104:105] neg_lo:[0,1] neg_hi:[0,1]
	s_nop 0
	v_pk_add_f32 v[102:103], v[102:103], v[104:105]
	s_nop 0
	v_pk_add_f32 v[102:103], v[110:111], v[102:103]
	s_nop 0
	v_cndmask_b32_e32 v64, v94, v102, vcc
	v_cmp_neq_f32_e32 vcc, s33, v133
	s_nop 1
	v_cndmask_b32_e32 v102, v94, v103, vcc
	v_cmp_ngt_f32_e32 vcc, -1.0, v133
	s_nop 1
	v_cndmask_b32_e32 v102, v95, v102, vcc
	v_cmp_ngt_f32_e32 vcc, -1.0, v132
	s_nop 1
	v_cndmask_b32_e32 v64, v95, v64, vcc
	v_cmp_neq_f32_e32 vcc, -1.0, v132
	s_nop 1
	v_cndmask_b32_e32 v64, v96, v64, vcc
	v_cmp_neq_f32_e32 vcc, -1.0, v133
	s_nop 1
	v_cndmask_b32_e32 v102, v96, v102, vcc
	v_cmp_lt_f32_e64 vcc, |v133|, s23
	s_nop 1
	v_cndmask_b32_e32 v103, v102, v133, vcc
	v_cmp_lt_f32_e64 vcc, |v132|, s23
	s_nop 1
	v_cndmask_b32_e32 v102, v64, v132, vcc
	v_add_f32_e32 v64, v88, v97
	v_mul_f32_e64 v88, |v64|, s19
	v_exp_f32_e32 v128, v88
	v_pk_add_f32 v[100:101], v[100:101], v[102:103] neg_lo:[0,1] neg_hi:[0,1]
	v_mul_f32_e64 v102, |v89|, s19
	v_pk_mul_f32 v[100:101], v[100:101], s[22:23] op_sel_hi:[1,0]
	v_min_f32_e32 v88, 0, v64
	v_add_f32_e32 v64, 1.0, v128
	v_exp_f32_e32 v129, v102
	global_store_dwordx4 v[86:87], v[98:101], off offset:256
	v_min_f32_e32 v89, 0, v89
	v_add_f32_e32 v104, 1.0, v129
	v_cvt_f64_f32_e32 v[98:99], v64
	v_frexp_exp_i32_f64_e32 v100, v[98:99]
	v_add_f32_e32 v98, -1.0, v64
	v_sub_f32_e32 v99, v128, v98
	v_sub_f32_e32 v98, v98, v64
	v_add_f32_e32 v98, 1.0, v98
	v_add_f32_e32 v102, v99, v98
	v_cvt_f64_f32_e32 v[98:99], v104
	v_frexp_exp_i32_f64_e32 v98, v[98:99]
	v_frexp_mant_f32_e32 v99, v104
	v_cmp_gt_f32_e32 vcc, s21, v99
	v_frexp_mant_f32_e32 v101, v64
	v_add_f32_e32 v103, -1.0, v104
	v_subbrev_co_u32_e32 v99, vcc, 0, v98, vcc
	v_cmp_gt_f32_e32 vcc, s21, v101
	v_sub_f32_e32 v105, v129, v103
	v_sub_f32_e32 v103, v103, v104
	v_subbrev_co_u32_e32 v101, vcc, 0, v100, vcc
	v_sub_u32_e32 v100, 0, v101
	v_add_f32_e32 v103, 1.0, v103
	v_ldexp_f32 v98, v64, v100
	v_sub_u32_e32 v64, 0, v99
	v_add_f32_e32 v105, v105, v103
	v_cvt_f32_i32_e32 v103, v99
	v_ldexp_f32 v99, v104, v64
	v_pk_add_f32 v[114:115], v[98:99], 1.0 op_sel_hi:[1,0]
	v_ldexp_f32 v100, v102, v100
	v_pk_add_f32 v[116:117], v[114:115], -1.0 op_sel_hi:[1,0]
	v_cvt_f32_i32_e32 v102, v101
	v_ldexp_f32 v101, v105, v64
	v_pk_add_f32 v[116:117], v[98:99], v[116:117] neg_lo:[0,1] neg_hi:[0,1]
	v_pk_add_f32 v[110:111], v[98:99], -1.0 op_sel_hi:[1,0]
	v_pk_add_f32 v[116:117], v[100:101], v[116:117]
	v_pk_add_f32 v[112:113], v[110:111], 1.0 op_sel_hi:[1,0]
	v_pk_add_f32 v[118:119], v[114:115], v[116:117]
	v_pk_add_f32 v[98:99], v[98:99], v[112:113] neg_lo:[0,1] neg_hi:[0,1]
	v_rcp_f32_e32 v120, v118
	v_rcp_f32_e32 v121, v119
	v_pk_add_f32 v[98:99], v[100:101], v[98:99]
	v_pk_add_f32 v[114:115], v[118:119], v[114:115] neg_lo:[0,1] neg_hi:[0,1]
	v_pk_add_f32 v[100:101], v[110:111], v[98:99]
	v_pk_add_f32 v[114:115], v[116:117], v[114:115] neg_lo:[0,1] neg_hi:[0,1]
	v_pk_mul_f32 v[112:113], v[100:101], v[120:121]
	v_pk_add_f32 v[110:111], v[100:101], v[110:111] neg_lo:[0,1] neg_hi:[0,1]
	v_pk_mul_f32 v[122:123], v[118:119], v[112:113]
	v_pk_add_f32 v[98:99], v[98:99], v[110:111] neg_lo:[0,1] neg_hi:[0,1]
	v_pk_fma_f32 v[116:117], v[112:113], v[118:119], v[122:123] neg_lo:[0,0,1] neg_hi:[0,0,1]
	v_pk_mul_f32 v[104:105], v[102:103], s[12:13] op_sel_hi:[1,0]
; __device__ __forceinline__ void p1_side_task(int c, LAS unsigned char* lds, const bf16_t* XN, const bf16_t* WIN, const float* b_f, float* LF, bf16_t* Kb, bf16_t* Vb, bf16_t* P1b) {
;     ...
;             for (int j = 0; j < 4; ++j) { const float xx = acc[g][j] + bfh; const float v = (fminf(xx, 0.f) - log1pf(__expf(-fabsf(xx)))) * LOG2E; const int m = 4 * fq + j;
;                 if (g < 2) { const int row = 32 * c + 16 * g + m; LF[(size_t)((row >> 12) * NH + fr) * KVROWS + 64 + (row & 4095)] = v; }
	v_pk_fma_f32 v[116:117], v[112:113], v[114:115], v[116:117]
	v_pk_fma_f32 v[106:107], v[102:103], s[12:13], v[104:105] op_sel_hi:[1,0,1] neg_lo:[0,0,1] neg_hi:[0,0,1]
	v_pk_add_f32 v[124:125], v[122:123], v[116:117]
	v_pk_fma_f32 v[102:103], v[102:103], s[14:15], v[106:107] op_sel_hi:[1,0,1]
	v_pk_add_f32 v[126:127], v[100:101], v[124:125] neg_lo:[0,1] neg_hi:[0,1]
	v_pk_add_f32 v[122:123], v[124:125], v[122:123] neg_lo:[0,1] neg_hi:[0,1]
	v_pk_add_f32 v[100:101], v[100:101], v[126:127] neg_lo:[0,1] neg_hi:[0,1]
	v_pk_add_f32 v[116:117], v[122:123], v[116:117] neg_lo:[0,1] neg_hi:[0,1]
	v_pk_add_f32 v[100:101], v[100:101], v[124:125] neg_lo:[0,1] neg_hi:[0,1]
	v_pk_add_f32 v[106:107], v[104:105], v[102:103]
	v_pk_add_f32 v[98:99], v[98:99], v[100:101]
	v_pk_add_f32 v[108:109], v[106:107], v[104:105] neg_lo:[0,1] neg_hi:[0,1]
	v_pk_add_f32 v[98:99], v[116:117], v[98:99]
	v_mov_b32_e32 v104, v106
	v_pk_add_f32 v[100:101], v[126:127], v[98:99]
	v_cmp_neq_f32_e32 vcc, s33, v128
	v_pk_mul_f32 v[110:111], v[120:121], v[100:101]
	s_nop 0
	v_pk_mul_f32 v[116:117], v[118:119], v[110:111]
	v_pk_add_f32 v[122:123], v[112:113], v[110:111]
	v_pk_fma_f32 v[118:119], v[110:111], v[118:119], v[116:117] neg_lo:[0,0,1] neg_hi:[0,0,1]
	v_pk_add_f32 v[112:113], v[122:123], v[112:113] neg_lo:[0,1] neg_hi:[0,1]
	s_nop 0
	v_pk_add_f32 v[112:113], v[110:111], v[112:113] neg_lo:[0,1] neg_hi:[0,1]
	v_pk_fma_f32 v[110:111], v[110:111], v[114:115], v[118:119]
	s_nop 0
	v_pk_add_f32 v[114:115], v[116:117], v[110:111]
	s_nop 0
	v_pk_add_f32 v[118:119], v[100:101], v[114:115] neg_lo:[0,1] neg_hi:[0,1]
	v_pk_add_f32 v[116:117], v[114:115], v[116:117] neg_lo:[0,1] neg_hi:[0,1]
	s_nop 0
	v_pk_add_f32 v[110:111], v[116:117], v[110:111] neg_lo:[0,1] neg_hi:[0,1]
	v_pk_add_f32 v[116:117], v[126:127], v[100:101] neg_lo:[0,1] neg_hi:[0,1]
	v_pk_add_f32 v[100:101], v[100:101], v[118:119] neg_lo:[0,1] neg_hi:[0,1]
	v_pk_add_f32 v[98:99], v[98:99], v[116:117]
	v_pk_add_f32 v[100:101], v[100:101], v[114:115] neg_lo:[0,1] neg_hi:[0,1]
	v_mov_b32_e32 v117, v107
	v_pk_add_f32 v[98:99], v[98:99], v[100:101]
	s_nop 0
	v_pk_add_f32 v[98:99], v[110:111], v[98:99]
	s_nop 0
	v_pk_add_f32 v[98:99], v[118:119], v[98:99]
	s_nop 0
	v_pk_mul_f32 v[98:99], v[120:121], v[98:99]
	s_nop 0
	v_pk_add_f32 v[98:99], v[112:113], v[98:99]
	s_nop 0
	v_pk_add_f32 v[100:101], v[122:123], v[98:99]
	s_nop 0
	v_pk_add_f32 v[112:113], v[100:101], v[122:123] neg_lo:[0,1] neg_hi:[0,1]
	v_ldexp_f32 v110, v100, 1
	v_pk_add_f32 v[98:99], v[98:99], v[112:113] neg_lo:[0,1] neg_hi:[0,1]
	v_pk_mul_f32 v[112:113], v[100:101], v[100:101]
	v_ldexp_f32 v111, v101, 1
	v_pk_fma_f32 v[114:115], v[112:113], s[18:19], v[84:85] op_sel_hi:[1,0,0]
	v_pk_mul_f32 v[100:101], v[100:101], v[112:113]
	v_pk_fma_f32 v[112:113], v[112:113], v[114:115], s[20:21] op_sel_hi:[1,1,0]
	v_ldexp_f32 v98, v98, 1
	v_pk_mul_f32 v[100:101], v[100:101], v[112:113]
	v_ldexp_f32 v99, v99, 1
	v_pk_add_f32 v[112:113], v[110:111], v[100:101]
	s_nop 0
	v_pk_add_f32 v[110:111], v[112:113], v[110:111] neg_lo:[0,1] neg_hi:[0,1]
	s_nop 0
	v_pk_add_f32 v[100:101], v[100:101], v[110:111] neg_lo:[0,1] neg_hi:[0,1]
	s_nop 0
	v_pk_add_f32 v[98:99], v[98:99], v[100:101]
	s_nop 0
	v_pk_add_f32 v[100:101], v[112:113], v[98:99]
	s_nop 0
	v_pk_add_f32 v[114:115], v[106:107], v[100:101]
	v_pk_add_f32 v[110:111], v[100:101], v[112:113] neg_lo:[0,1] neg_hi:[0,1]
	v_mov_b32_e32 v116, v114
	v_pk_add_f32 v[104:105], v[116:117], v[104:105] neg_lo:[0,1] neg_hi:[0,1]
	v_mov_b32_e32 v116, v100
	v_mov_b32_e32 v117, v103
	v_pk_add_f32 v[116:117], v[116:117], v[104:105] neg_lo:[0,1] neg_hi:[0,1]
	v_mov_b32_e32 v109, v105
	v_mov_b32_e32 v100, v114
	v_mov_b32_e32 v105, v113
	v_pk_add_f32 v[104:105], v[100:101], v[104:105] neg_lo:[0,1] neg_hi:[0,1]
	v_mov_b32_e32 v112, v106
	v_mov_b32_e32 v113, v99
	v_mov_b32_e32 v111, v105
	v_pk_add_f32 v[120:121], v[114:115], v[106:107] neg_lo:[0,1] neg_hi:[0,1]
	v_pk_add_f32 v[112:113], v[112:113], v[104:105] neg_lo:[0,1] neg_hi:[0,1]
	v_pk_add_f32 v[104:105], v[98:99], v[110:111] neg_lo:[0,1] neg_hi:[0,1]
	v_mov_b32_e32 v99, v101
	v_pk_add_f32 v[100:101], v[114:115], v[120:121] neg_lo:[0,1] neg_hi:[0,1]
	v_pk_add_f32 v[118:119], v[102:103], v[108:109] neg_lo:[0,1] neg_hi:[0,1]
	v_mov_b32_e32 v111, v121
	v_mov_b32_e32 v103, v107
	v_mov_b32_e32 v109, v101
	v_pk_add_f32 v[98:99], v[98:99], v[110:111] neg_lo:[0,1] neg_hi:[0,1]
	v_pk_add_f32 v[100:101], v[102:103], v[108:109] neg_lo:[0,1] neg_hi:[0,1]
	v_pk_add_f32 v[112:113], v[116:117], v[112:113]
	v_pk_add_f32 v[98:99], v[98:99], v[100:101]
	v_mov_b32_e32 v101, v117
	v_pk_add_f32 v[102:103], v[112:113], v[98:99]
	v_mov_b32_e32 v99, v113
	v_pk_add_f32 v[100:101], v[98:99], v[100:101] neg_lo:[0,1] neg_hi:[0,1]
	v_pk_add_f32 v[106:107], v[114:115], v[102:103]
	v_pk_add_f32 v[98:99], v[98:99], v[100:101] neg_lo:[0,1] neg_hi:[0,1]
	v_pk_add_f32 v[104:105], v[104:105], v[100:101] neg_lo:[0,1] neg_hi:[0,1]
	v_pk_add_f32 v[98:99], v[118:119], v[98:99] neg_lo:[0,1] neg_hi:[0,1]
	v_pk_add_f32 v[100:101], v[106:107], v[114:115] neg_lo:[0,1] neg_hi:[0,1]
	v_pk_add_f32 v[98:99], v[104:105], v[98:99]
	v_pk_add_f32 v[100:101], v[102:103], v[100:101] neg_lo:[0,1] neg_hi:[0,1]
	v_mul_f32_e64 v102, |v83|, s19
	v_pk_add_f32 v[98:99], v[98:99], v[100:101]
	v_min_f32_e32 v83, 0, v83
	v_pk_add_f32 v[98:99], v[106:107], v[98:99]
	s_nop 0
	v_cndmask_b32_e32 v64, v94, v98, vcc
	v_cmp_neq_f32_e32 vcc, s33, v129
	s_nop 1
	v_cndmask_b32_e32 v98, v94, v99, vcc
	v_cmp_ngt_f32_e32 vcc, -1.0, v129
	s_nop 1
	v_cndmask_b32_e32 v98, v95, v98, vcc
	v_cmp_ngt_f32_e32 vcc, -1.0, v128
	s_nop 1
	v_cndmask_b32_e32 v64, v95, v64, vcc
; __device__ __forceinline__ void p1_side_task(int c, LAS unsigned char* lds, const bf16_t* XN, const bf16_t* WIN, const float* b_f, float* LF, bf16_t* Kb, bf16_t* Vb, bf16_t* P1b) {
;     ...
;             for (int j = 0; j < 4; ++j) { const float xx = acc[g][j] + bfh; const float v = (fminf(xx, 0.f) - log1pf(__expf(-fabsf(xx)))) * LOG2E; const int m = 4 * fq + j;
;                 if (g < 2) { const int row = 32 * c + 16 * g + m; LF[(size_t)((row >> 12) * NH + fr) * KVROWS + 64 + (row & 4095)] = v; }
	v_cmp_neq_f32_e32 vcc, -1.0, v128
	s_nop 1
	v_cndmask_b32_e32 v64, v96, v64, vcc
	v_cmp_neq_f32_e32 vcc, -1.0, v129
	s_nop 1
	v_cndmask_b32_e32 v98, v96, v98, vcc
	v_cmp_lt_f32_e64 vcc, |v129|, s23
	s_nop 1
	v_cndmask_b32_e32 v99, v98, v129, vcc
	v_cmp_lt_f32_e64 vcc, |v128|, s23
	v_exp_f32_e32 v129, v102
	s_nop 0
	v_cndmask_b32_e32 v98, v64, v128, vcc
	v_add_f32_e32 v64, v82, v97
	v_mul_f32_e64 v82, |v64|, s19
	v_exp_f32_e32 v128, v82
	v_pk_add_f32 v[88:89], v[88:89], v[98:99] neg_lo:[0,1] neg_hi:[0,1]
	v_min_f32_e32 v82, 0, v64
	v_pk_mul_f32 v[98:99], v[88:89], s[22:23] op_sel_hi:[1,0]
	v_add_f32_e32 v64, 1.0, v128
	v_cvt_f64_f32_e32 v[88:89], v64
	v_frexp_exp_i32_f64_e32 v100, v[88:89]
	v_add_f32_e32 v88, -1.0, v64
	v_sub_f32_e32 v89, v128, v88
	v_sub_f32_e32 v88, v88, v64
	v_add_f32_e32 v88, 1.0, v88
	v_add_f32_e32 v104, 1.0, v129
	v_add_f32_e32 v102, v89, v88
	v_cvt_f64_f32_e32 v[88:89], v104
	v_frexp_exp_i32_f64_e32 v88, v[88:89]
	v_frexp_mant_f32_e32 v89, v104
	v_cmp_gt_f32_e32 vcc, s21, v89
	v_frexp_mant_f32_e32 v101, v64
	v_add_f32_e32 v103, -1.0, v104
	v_subbrev_co_u32_e32 v89, vcc, 0, v88, vcc
	v_cmp_gt_f32_e32 vcc, s21, v101
	v_sub_f32_e32 v105, v129, v103
	v_sub_f32_e32 v103, v103, v104
	v_subbrev_co_u32_e32 v101, vcc, 0, v100, vcc
	v_sub_u32_e32 v100, 0, v101
	v_add_f32_e32 v103, 1.0, v103
	v_ldexp_f32 v88, v64, v100
	v_sub_u32_e32 v64, 0, v89
	v_add_f32_e32 v105, v105, v103
	v_cvt_f32_i32_e32 v103, v89
	v_ldexp_f32 v89, v104, v64
	v_pk_add_f32 v[114:115], v[88:89], 1.0 op_sel_hi:[1,0]
	v_ldexp_f32 v100, v102, v100
	v_pk_add_f32 v[116:117], v[114:115], -1.0 op_sel_hi:[1,0]
	v_cvt_f32_i32_e32 v102, v101
	v_ldexp_f32 v101, v105, v64
	v_pk_add_f32 v[116:117], v[88:89], v[116:117] neg_lo:[0,1] neg_hi:[0,1]
	v_pk_add_f32 v[110:111], v[88:89], -1.0 op_sel_hi:[1,0]
	v_pk_add_f32 v[116:117], v[100:101], v[116:117]
	v_pk_add_f32 v[112:113], v[110:111], 1.0 op_sel_hi:[1,0]
	v_pk_add_f32 v[118:119], v[114:115], v[116:117]
	v_pk_add_f32 v[88:89], v[88:89], v[112:113] neg_lo:[0,1] neg_hi:[0,1]
	v_rcp_f32_e32 v120, v118
	v_rcp_f32_e32 v121, v119
	v_pk_add_f32 v[88:89], v[100:101], v[88:89]
	v_pk_add_f32 v[114:115], v[118:119], v[114:115] neg_lo:[0,1] neg_hi:[0,1]
	v_pk_add_f32 v[100:101], v[110:111], v[88:89]
	v_pk_add_f32 v[114:115], v[116:117], v[114:115] neg_lo:[0,1] neg_hi:[0,1]
	v_pk_mul_f32 v[112:113], v[100:101], v[120:121]
	v_pk_add_f32 v[110:111], v[100:101], v[110:111] neg_lo:[0,1] neg_hi:[0,1]
	v_pk_mul_f32 v[122:123], v[118:119], v[112:113]
	v_pk_add_f32 v[88:89], v[88:89], v[110:111] neg_lo:[0,1] neg_hi:[0,1]
	v_pk_fma_f32 v[116:117], v[112:113], v[118:119], v[122:123] neg_lo:[0,0,1] neg_hi:[0,0,1]
	v_pk_mul_f32 v[104:105], v[102:103], s[12:13] op_sel_hi:[1,0]
	v_pk_fma_f32 v[116:117], v[112:113], v[114:115], v[116:117]
	v_pk_fma_f32 v[106:107], v[102:103], s[12:13], v[104:105] op_sel_hi:[1,0,1] neg_lo:[0,0,1] neg_hi:[0,0,1]
	v_pk_add_f32 v[124:125], v[122:123], v[116:117]
	v_pk_fma_f32 v[102:103], v[102:103], s[14:15], v[106:107] op_sel_hi:[1,0,1]
	v_pk_add_f32 v[126:127], v[100:101], v[124:125] neg_lo:[0,1] neg_hi:[0,1]
	v_pk_add_f32 v[122:123], v[124:125], v[122:123] neg_lo:[0,1] neg_hi:[0,1]
	v_pk_add_f32 v[100:101], v[100:101], v[126:127] neg_lo:[0,1] neg_hi:[0,1]
	v_pk_add_f32 v[116:117], v[122:123], v[116:117] neg_lo:[0,1] neg_hi:[0,1]
	v_pk_add_f32 v[100:101], v[100:101], v[124:125] neg_lo:[0,1] neg_hi:[0,1]
	v_pk_add_f32 v[106:107], v[104:105], v[102:103]
	v_pk_add_f32 v[88:89], v[88:89], v[100:101]
	v_pk_add_f32 v[108:109], v[106:107], v[104:105] neg_lo:[0,1] neg_hi:[0,1]
	v_pk_add_f32 v[88:89], v[116:117], v[88:89]
	v_mov_b32_e32 v104, v106
	v_pk_add_f32 v[100:101], v[126:127], v[88:89]
	v_cmp_neq_f32_e32 vcc, s33, v128
	v_pk_mul_f32 v[110:111], v[120:121], v[100:101]
	s_nop 0
	v_pk_mul_f32 v[116:117], v[118:119], v[110:111]
	v_pk_add_f32 v[122:123], v[112:113], v[110:111]
	v_pk_fma_f32 v[118:119], v[110:111], v[118:119], v[116:117] neg_lo:[0,0,1] neg_hi:[0,0,1]
	v_pk_add_f32 v[112:113], v[122:123], v[112:113] neg_lo:[0,1] neg_hi:[0,1]
	s_nop 0
	v_pk_add_f32 v[112:113], v[110:111], v[112:113] neg_lo:[0,1] neg_hi:[0,1]
	v_pk_fma_f32 v[110:111], v[110:111], v[114:115], v[118:119]
	s_nop 0
	v_pk_add_f32 v[114:115], v[116:117], v[110:111]
	s_nop 0
	v_pk_add_f32 v[118:119], v[100:101], v[114:115] neg_lo:[0,1] neg_hi:[0,1]
	v_pk_add_f32 v[116:117], v[114:115], v[116:117] neg_lo:[0,1] neg_hi:[0,1]
	s_nop 0
	v_pk_add_f32 v[110:111], v[116:117], v[110:111] neg_lo:[0,1] neg_hi:[0,1]
	v_pk_add_f32 v[116:117], v[126:127], v[100:101] neg_lo:[0,1] neg_hi:[0,1]
	v_pk_add_f32 v[100:101], v[100:101], v[118:119] neg_lo:[0,1] neg_hi:[0,1]
	v_pk_add_f32 v[88:89], v[88:89], v[116:117]
	v_pk_add_f32 v[100:101], v[100:101], v[114:115] neg_lo:[0,1] neg_hi:[0,1]
	v_mov_b32_e32 v115, v107
	v_pk_add_f32 v[88:89], v[88:89], v[100:101]
	s_nop 0
	v_pk_add_f32 v[88:89], v[110:111], v[88:89]
	s_nop 0
	v_pk_add_f32 v[88:89], v[118:119], v[88:89]
	s_nop 0
	v_pk_mul_f32 v[88:89], v[120:121], v[88:89]
	s_nop 0
	v_pk_add_f32 v[88:89], v[112:113], v[88:89]
	s_nop 0
	v_pk_add_f32 v[100:101], v[122:123], v[88:89]
	s_nop 0
	v_pk_add_f32 v[112:113], v[100:101], v[122:123] neg_lo:[0,1] neg_hi:[0,1]
	v_ldexp_f32 v110, v100, 1
	v_pk_add_f32 v[88:89], v[88:89], v[112:113] neg_lo:[0,1] neg_hi:[0,1]
	v_pk_mul_f32 v[112:113], v[100:101], v[100:101]
	v_ldexp_f32 v111, v101, 1
	v_pk_fma_f32 v[84:85], v[112:113], s[18:19], v[84:85] op_sel_hi:[1,0,0]
	v_pk_mul_f32 v[100:101], v[100:101], v[112:113]
	v_pk_fma_f32 v[84:85], v[112:113], v[84:85], s[20:21] op_sel_hi:[1,1,0]
	v_ldexp_f32 v88, v88, 1
	v_pk_mul_f32 v[84:85], v[100:101], v[84:85]
	v_ldexp_f32 v89, v89, 1
; __device__ __forceinline__ void p1_side_task(int c, LAS unsigned char* lds, const bf16_t* XN, const bf16_t* WIN, const float* b_f, float* LF, bf16_t* Kb, bf16_t* Vb, bf16_t* P1b) {
;     ...
;         for (int g = 0; g < 5; ++g) { f32x4 s = red[g * 64 + lane];
; #pragma unroll
;             for (int ww = 1; ww < 8; ++ww) s += red[(ww * 5 + g) * 64 + lane];
;             acc[g] = s; }
;     ...
;             for (int j = 0; j < 4; ++j) { const float xx = acc[g][j] + bfh; const float v = (fminf(xx, 0.f) - log1pf(__expf(-fabsf(xx)))) * LOG2E; const int m = 4 * fq + j;
;                 if (g < 2) { const int row = 32 * c + 16 * g + m; LF[(size_t)((row >> 12) * NH + fr) * KVROWS + 64 + (row & 4095)] = v; }
;                 else if (c == 0) { LF[(size_t)fr * KVROWS + 48 + m] = v; LF[(size_t)(NH + fr) * KVROWS + 48 + m] = v; } }
	v_pk_add_f32 v[100:101], v[110:111], v[84:85]
	s_nop 0
	v_pk_add_f32 v[110:111], v[100:101], v[110:111] neg_lo:[0,1] neg_hi:[0,1]
	s_nop 0
	v_pk_add_f32 v[84:85], v[84:85], v[110:111] neg_lo:[0,1] neg_hi:[0,1]
	s_nop 0
	v_pk_add_f32 v[84:85], v[88:89], v[84:85]
	s_nop 0
	v_pk_add_f32 v[88:89], v[100:101], v[84:85]
	s_nop 0
	v_pk_add_f32 v[112:113], v[106:107], v[88:89]
	v_pk_add_f32 v[110:111], v[88:89], v[100:101] neg_lo:[0,1] neg_hi:[0,1]
	v_mov_b32_e32 v114, v112
	v_pk_add_f32 v[104:105], v[114:115], v[104:105] neg_lo:[0,1] neg_hi:[0,1]
	v_mov_b32_e32 v114, v88
	v_mov_b32_e32 v115, v103
	v_pk_add_f32 v[114:115], v[114:115], v[104:105] neg_lo:[0,1] neg_hi:[0,1]
	v_mov_b32_e32 v109, v105
	v_mov_b32_e32 v88, v112
	v_mov_b32_e32 v105, v101
	v_pk_add_f32 v[100:101], v[88:89], v[104:105] neg_lo:[0,1] neg_hi:[0,1]
	v_mov_b32_e32 v104, v106
	v_mov_b32_e32 v105, v85
	v_mov_b32_e32 v111, v101
	v_pk_add_f32 v[118:119], v[112:113], v[106:107] neg_lo:[0,1] neg_hi:[0,1]
	v_pk_add_f32 v[104:105], v[104:105], v[100:101] neg_lo:[0,1] neg_hi:[0,1]
	v_pk_add_f32 v[100:101], v[84:85], v[110:111] neg_lo:[0,1] neg_hi:[0,1]
	v_mov_b32_e32 v85, v89
	v_pk_add_f32 v[88:89], v[112:113], v[118:119] neg_lo:[0,1] neg_hi:[0,1]
	v_pk_add_f32 v[116:117], v[102:103], v[108:109] neg_lo:[0,1] neg_hi:[0,1]
	v_mov_b32_e32 v111, v119
	v_mov_b32_e32 v103, v107
	v_mov_b32_e32 v109, v89
	v_pk_add_f32 v[84:85], v[84:85], v[110:111] neg_lo:[0,1] neg_hi:[0,1]
	v_pk_add_f32 v[88:89], v[102:103], v[108:109] neg_lo:[0,1] neg_hi:[0,1]
	v_pk_add_f32 v[104:105], v[114:115], v[104:105]
	v_pk_add_f32 v[84:85], v[84:85], v[88:89]
	v_mov_b32_e32 v89, v115
	v_pk_add_f32 v[102:103], v[104:105], v[84:85]
	v_mov_b32_e32 v85, v105
	v_pk_add_f32 v[88:89], v[84:85], v[88:89] neg_lo:[0,1] neg_hi:[0,1]
	v_pk_add_f32 v[106:107], v[112:113], v[102:103]
	v_pk_add_f32 v[84:85], v[84:85], v[88:89] neg_lo:[0,1] neg_hi:[0,1]
	v_pk_add_f32 v[100:101], v[100:101], v[88:89] neg_lo:[0,1] neg_hi:[0,1]
	v_pk_add_f32 v[84:85], v[116:117], v[84:85] neg_lo:[0,1] neg_hi:[0,1]
	v_pk_add_f32 v[88:89], v[106:107], v[112:113] neg_lo:[0,1] neg_hi:[0,1]
	v_pk_add_f32 v[84:85], v[100:101], v[84:85]
	v_pk_add_f32 v[88:89], v[102:103], v[88:89] neg_lo:[0,1] neg_hi:[0,1]
	s_nop 0
	v_pk_add_f32 v[84:85], v[84:85], v[88:89]
	s_nop 0
	v_pk_add_f32 v[84:85], v[106:107], v[84:85]
	s_nop 0
	v_cndmask_b32_e32 v64, v94, v84, vcc
	v_cmp_neq_f32_e32 vcc, s33, v129
	s_nop 1
	v_cndmask_b32_e32 v84, v94, v85, vcc
	v_cmp_ngt_f32_e32 vcc, -1.0, v129
	s_nop 1
	v_cndmask_b32_e32 v84, v95, v84, vcc
	v_cmp_ngt_f32_e32 vcc, -1.0, v128
	s_nop 1
	v_cndmask_b32_e32 v64, v95, v64, vcc
	v_cmp_neq_f32_e32 vcc, -1.0, v128
	s_nop 1
	v_cndmask_b32_e32 v64, v96, v64, vcc
	v_cmp_neq_f32_e32 vcc, -1.0, v129
	s_nop 1
	v_cndmask_b32_e32 v84, v96, v84, vcc
	v_cmp_lt_f32_e64 vcc, |v129|, s23
	s_nop 1
	v_cndmask_b32_e32 v85, v84, v129, vcc
	v_cmp_lt_f32_e64 vcc, |v128|, s23
	s_nop 1
	v_cndmask_b32_e32 v84, v64, v128, vcc
	v_pk_add_f32 v[82:83], v[82:83], v[84:85] neg_lo:[0,1] neg_hi:[0,1]
	s_nop 0
	v_pk_mul_f32 v[100:101], v[82:83], s[22:23] op_sel_hi:[1,0]
	global_store_dwordx4 v[86:87], v[98:101], off offset:320
	s_cbranch_scc1 .LBB0_426
	ds_read_b128 v[82:85], v91 offset:2048
	ds_read_b128 v[86:89], v91 offset:7168
	ds_read_b128 v[98:101], v91 offset:12288
	ds_read_b128 v[102:105], v91 offset:17408
	ds_read_b128 v[106:109], v91 offset:22528
	ds_read_b128 v[110:113], v91 offset:27648
	ds_read_b128 v[114:117], v91 offset:32768
	ds_read_b128 v[118:121], v91 offset:37888
	s_waitcnt lgkmcnt(6)
	v_pk_add_f32 v[82:83], v[82:83], v[86:87]
	v_pk_add_f32 v[84:85], v[84:85], v[88:89]
	s_waitcnt lgkmcnt(5)
	v_pk_add_f32 v[82:83], v[82:83], v[98:99]
	v_pk_add_f32 v[84:85], v[84:85], v[100:101]
	s_waitcnt lgkmcnt(4)
	v_pk_add_f32 v[82:83], v[82:83], v[102:103]
	s_waitcnt lgkmcnt(3)
	v_pk_add_f32 v[82:83], v[82:83], v[106:107]
	s_waitcnt lgkmcnt(2)
	v_pk_add_f32 v[82:83], v[82:83], v[110:111]
	s_waitcnt lgkmcnt(1)
	v_pk_add_f32 v[82:83], v[82:83], v[114:115]
	s_waitcnt lgkmcnt(0)
	v_pk_add_f32 v[86:87], v[82:83], v[118:119]
	s_nop 0
	v_add_f32_e32 v64, v86, v97
	v_mul_f32_e64 v82, |v64|, s19
	v_exp_f32_e32 v86, v82
	v_pk_add_f32 v[82:83], v[84:85], v[104:105]
	v_add_f32_e32 v87, v87, v97
	v_min_f32_e32 v64, 0, v64
	v_add_f32_e32 v88, 1.0, v86
	v_cvt_f64_f32_e32 v[84:85], v88
	v_frexp_exp_i32_f64_e32 v84, v[84:85]
	v_frexp_mant_f32_e32 v85, v88
	v_cmp_gt_f32_e32 vcc, s21, v85
	v_add_f32_e32 v101, -1.0, v88
	v_sub_f32_e32 v102, v86, v101
	v_subbrev_co_u32_e32 v84, vcc, 0, v84, vcc
	v_cvt_f32_i32_e32 v85, v84
	v_sub_u32_e32 v84, 0, v84
	v_ldexp_f32 v99, v88, v84
	v_sub_f32_e32 v88, v101, v88
	v_add_f32_e32 v88, 1.0, v88
	v_add_f32_e32 v101, 1.0, v99
	v_add_f32_e32 v88, v102, v88
	v_add_f32_e32 v102, -1.0, v101
	v_ldexp_f32 v84, v88, v84
	v_sub_f32_e32 v102, v99, v102
	v_add_f32_e32 v102, v84, v102
	v_add_f32_e32 v100, -1.0, v99
	v_add_f32_e32 v103, v101, v102
	v_add_f32_e32 v88, 1.0, v100
	v_rcp_f32_e32 v104, v103
	v_sub_f32_e32 v88, v99, v88
	v_add_f32_e32 v84, v84, v88
	v_add_f32_e32 v88, v100, v84
	v_mul_f32_e32 v99, v88, v104
	v_mul_f32_e32 v105, v103, v99
	v_sub_f32_e32 v101, v103, v101
	v_sub_f32_e32 v101, v102, v101
	v_fma_f32 v102, v99, v103, -v105
	v_fmac_f32_e32 v102, v99, v101
	v_add_f32_e32 v106, v105, v102
	v_sub_f32_e32 v107, v88, v106
	v_sub_f32_e32 v100, v88, v100
	v_sub_f32_e32 v88, v88, v107
	v_sub_f32_e32 v105, v106, v105
	v_sub_f32_e32 v84, v84, v100
	v_sub_f32_e32 v88, v88, v106
	v_sub_f32_e32 v102, v105, v102
	v_add_f32_e32 v84, v84, v88
	v_add_f32_e32 v84, v102, v84
	v_add_f32_e32 v88, v107, v84
	v_mul_f32_e32 v100, v104, v88
	v_mul_f32_e32 v105, v103, v100
; __device__ __forceinline__ void p1_side_task(int c, LAS unsigned char* lds, const bf16_t* XN, const bf16_t* WIN, const float* b_f, float* LF, bf16_t* Kb, bf16_t* Vb, bf16_t* P1b) {
;     ...
;             for (int j = 0; j < 4; ++j) { const float xx = acc[g][j] + bfh; const float v = (fminf(xx, 0.f) - log1pf(__expf(-fabsf(xx)))) * LOG2E; const int m = 4 * fq + j;
;                 if (g < 2) { const int row = 32 * c + 16 * g + m; LF[(size_t)((row >> 12) * NH + fr) * KVROWS + 64 + (row & 4095)] = v; }
;                 else if (c == 0) { LF[(size_t)fr * KVROWS + 48 + m] = v; LF[(size_t)(NH + fr) * KVROWS + 48 + m] = v; } }
	v_add_f32_e32 v102, v99, v100
	v_fma_f32 v103, v100, v103, -v105
	v_sub_f32_e32 v99, v102, v99
	v_fmac_f32_e32 v103, v100, v101
	v_sub_f32_e32 v99, v100, v99
	v_add_f32_e32 v100, v105, v103
	v_sub_f32_e32 v101, v88, v100
	v_sub_f32_e32 v105, v100, v105
	v_sub_f32_e32 v103, v105, v103
	v_sub_f32_e32 v105, v107, v88
	v_sub_f32_e32 v88, v88, v101
	v_add_f32_e32 v84, v84, v105
	v_sub_f32_e32 v88, v88, v100
	v_add_f32_e32 v84, v84, v88
	v_add_f32_e32 v84, v103, v84
	v_add_f32_e32 v84, v101, v84
	v_mul_f32_e32 v84, v104, v84
	v_add_f32_e32 v84, v99, v84
	v_add_f32_e32 v88, v102, v84
	v_mul_f32_e32 v100, v88, v88
	v_fmamk_f32 v103, v100, 0x3e9b6dac, v93
	v_mul_f32_e32 v101, v88, v100
	v_fmaak_f32 v100, v100, v103, 0x3f2aaada
	v_ldexp_f32 v99, v88, 1
	v_mul_f32_e32 v100, v101, v100
	v_add_f32_e32 v101, v99, v100
	v_sub_f32_e32 v88, v88, v102
	v_mul_f32_e32 v89, 0x3f317218, v85
	v_sub_f32_e32 v84, v84, v88
	v_sub_f32_e32 v88, v101, v99
	v_fma_f32 v98, v85, s12, -v89
	v_ldexp_f32 v84, v84, 1
	v_sub_f32_e32 v88, v100, v88
	v_fmac_f32_e32 v98, 0xb102e308, v85
	v_add_f32_e32 v84, v84, v88
	v_add_f32_e32 v85, v89, v98
	v_add_f32_e32 v88, v101, v84
	v_add_f32_e32 v99, v85, v88
	v_sub_f32_e32 v89, v85, v89
	v_sub_f32_e32 v89, v98, v89
	v_sub_f32_e32 v98, v88, v101
	v_sub_f32_e32 v100, v99, v85
	v_sub_f32_e32 v84, v84, v98
	v_sub_f32_e32 v88, v88, v100
	v_sub_f32_e32 v100, v99, v100
	v_add_f32_e32 v98, v89, v84
	v_sub_f32_e32 v85, v85, v100
	v_add_f32_e32 v85, v88, v85
	v_sub_f32_e32 v100, v98, v89
	v_add_f32_e32 v85, v98, v85
	v_sub_f32_e32 v98, v98, v100
	v_add_f32_e32 v88, v99, v85
	v_sub_f32_e32 v84, v84, v100
	v_sub_f32_e32 v89, v89, v98
	v_add_f32_e32 v84, v84, v89
	v_sub_f32_e32 v89, v88, v99
	v_sub_f32_e32 v85, v85, v89
	v_add_f32_e32 v84, v84, v85
	v_mul_f32_e64 v85, |v87|, s19
	v_add_f32_e32 v84, v88, v84
	v_cmp_neq_f32_e32 vcc, s33, v86
	v_exp_f32_e32 v88, v85
	v_pk_add_f32 v[82:83], v[82:83], v[108:109]
	v_cndmask_b32_e32 v84, v94, v84, vcc
	v_cmp_ngt_f32_e32 vcc, -1.0, v86
	v_pk_add_f32 v[82:83], v[82:83], v[112:113]
	s_nop 0
	v_cndmask_b32_e32 v84, v95, v84, vcc
	v_cmp_neq_f32_e32 vcc, -1.0, v86
	v_pk_add_f32 v[82:83], v[82:83], v[116:117]
	s_nop 0
	v_cndmask_b32_e32 v84, v96, v84, vcc
	v_cmp_lt_f32_e64 vcc, |v86|, s23
	v_pk_add_f32 v[82:83], v[82:83], v[120:121]
	s_nop 0
	v_cndmask_b32_e32 v84, v84, v86, vcc
	v_add_f32_e32 v86, 1.0, v88
	v_sub_f32_e32 v64, v64, v84
	v_cvt_f64_f32_e32 v[84:85], v86
	v_frexp_exp_i32_f64_e32 v84, v[84:85]
	v_frexp_mant_f32_e32 v85, v86
	v_cmp_gt_f32_e32 vcc, s21, v85
	v_add_f32_e32 v100, -1.0, v86
	v_sub_f32_e32 v101, v88, v100
	v_subbrev_co_u32_e32 v84, vcc, 0, v84, vcc
	v_cvt_f32_i32_e32 v85, v84
	v_sub_u32_e32 v84, 0, v84
	v_ldexp_f32 v98, v86, v84
	v_sub_f32_e32 v86, v100, v86
	v_add_f32_e32 v86, 1.0, v86
	v_add_f32_e32 v100, 1.0, v98
	v_add_f32_e32 v86, v101, v86
	v_add_f32_e32 v101, -1.0, v100
	v_ldexp_f32 v84, v86, v84
	v_sub_f32_e32 v101, v98, v101
	v_add_f32_e32 v101, v84, v101
	v_add_f32_e32 v99, -1.0, v98
	v_add_f32_e32 v102, v100, v101
	v_add_f32_e32 v86, 1.0, v99
	v_rcp_f32_e32 v103, v102
	v_sub_f32_e32 v86, v98, v86
	v_add_f32_e32 v84, v84, v86
	v_add_f32_e32 v86, v99, v84
	v_mul_f32_e32 v98, v86, v103
	v_mul_f32_e32 v104, v102, v98
	v_sub_f32_e32 v100, v102, v100
	v_sub_f32_e32 v100, v101, v100
	v_fma_f32 v101, v98, v102, -v104
	v_fmac_f32_e32 v101, v98, v100
	v_add_f32_e32 v105, v104, v101
	v_sub_f32_e32 v106, v86, v105
	v_sub_f32_e32 v99, v86, v99
	v_sub_f32_e32 v86, v86, v106
	v_sub_f32_e32 v104, v105, v104
	v_sub_f32_e32 v84, v84, v99
	v_sub_f32_e32 v86, v86, v105
	v_sub_f32_e32 v101, v104, v101
	v_add_f32_e32 v84, v84, v86
	v_add_f32_e32 v84, v101, v84
	v_add_f32_e32 v86, v106, v84
	v_mul_f32_e32 v99, v103, v86
	v_mul_f32_e32 v104, v102, v99
	v_add_f32_e32 v101, v98, v99
	v_fma_f32 v102, v99, v102, -v104
	v_sub_f32_e32 v98, v101, v98
	v_fmac_f32_e32 v102, v99, v100
	v_sub_f32_e32 v98, v99, v98
	v_add_f32_e32 v99, v104, v102
	v_sub_f32_e32 v100, v86, v99
	v_sub_f32_e32 v104, v99, v104
	v_sub_f32_e32 v102, v104, v102
	v_sub_f32_e32 v104, v106, v86
	v_sub_f32_e32 v86, v86, v100
	v_add_f32_e32 v84, v84, v104
	v_sub_f32_e32 v86, v86, v99
	v_add_f32_e32 v84, v84, v86
	v_add_f32_e32 v84, v102, v84
	v_add_f32_e32 v84, v100, v84
	v_mul_f32_e32 v84, v103, v84
	v_add_f32_e32 v84, v98, v84
	v_add_f32_e32 v86, v101, v84
	v_mul_f32_e32 v99, v86, v86
	v_fmamk_f32 v102, v99, 0x3e9b6dac, v93
	v_mul_f32_e32 v100, v86, v99
	v_fmaak_f32 v99, v99, v102, 0x3f2aaada
	v_ldexp_f32 v98, v86, 1
	v_mul_f32_e32 v99, v100, v99
	v_mul_f32_e32 v64, 0x3fb8aa3b, v64
	v_add_f32_e32 v100, v98, v99
	v_sub_f32_e32 v86, v86, v101
	global_store_dword v[68:69], v64, off offset:192
	global_store_dword v[70:71], v64, off
	v_min_f32_e32 v64, 0, v87
	v_mul_f32_e32 v87, 0x3f317218, v85
	v_sub_f32_e32 v84, v84, v86
	v_sub_f32_e32 v86, v100, v98
	v_fma_f32 v89, v85, s12, -v87
	v_ldexp_f32 v84, v84, 1
	v_sub_f32_e32 v86, v99, v86
	v_fmac_f32_e32 v89, 0xb102e308, v85
	v_add_f32_e32 v84, v84, v86
	v_add_f32_e32 v85, v87, v89
	v_add_f32_e32 v86, v100, v84
	v_add_f32_e32 v98, v85, v86
	v_sub_f32_e32 v87, v85, v87
	v_sub_f32_e32 v87, v89, v87
	v_sub_f32_e32 v89, v86, v100
	v_sub_f32_e32 v99, v98, v85
	v_sub_f32_e32 v84, v84, v89
	v_sub_f32_e32 v86, v86, v99
	v_sub_f32_e32 v99, v98, v99
	v_add_f32_e32 v89, v87, v84
	v_sub_f32_e32 v85, v85, v99
	v_add_f32_e32 v85, v86, v85
	v_sub_f32_e32 v99, v89, v87
	v_add_f32_e32 v85, v89, v85
	v_sub_f32_e32 v89, v89, v99
	v_add_f32_e32 v86, v98, v85
	v_sub_f32_e32 v84, v84, v99
	v_sub_f32_e32 v87, v87, v89
	v_add_f32_e32 v84, v84, v87
	v_sub_f32_e32 v87, v86, v98
	v_sub_f32_e32 v85, v85, v87
; __device__ __forceinline__ void p1_side_task(int c, LAS unsigned char* lds, const bf16_t* XN, const bf16_t* WIN, const float* b_f, float* LF, bf16_t* Kb, bf16_t* Vb, bf16_t* P1b) {
;     ...
;             for (int j = 0; j < 4; ++j) { const float xx = acc[g][j] + bfh; const float v = (fminf(xx, 0.f) - log1pf(__expf(-fabsf(xx)))) * LOG2E; const int m = 4 * fq + j;
;                 if (g < 2) { const int row = 32 * c + 16 * g + m; LF[(size_t)((row >> 12) * NH + fr) * KVROWS + 64 + (row & 4095)] = v; }
;                 else if (c == 0) { LF[(size_t)fr * KVROWS + 48 + m] = v; LF[(size_t)(NH + fr) * KVROWS + 48 + m] = v; } }
	v_add_f32_e32 v82, v82, v97
	v_add_f32_e32 v84, v84, v85
	v_mul_f32_e64 v85, |v82|, s19
	v_add_f32_e32 v84, v86, v84
	v_cmp_neq_f32_e32 vcc, s33, v88
	v_exp_f32_e32 v86, v85
	s_nop 0
	v_cndmask_b32_e32 v84, v94, v84, vcc
	v_cmp_ngt_f32_e32 vcc, -1.0, v88
	v_add_f32_e32 v87, 1.0, v86
	v_add_f32_e32 v99, -1.0, v87
	v_cndmask_b32_e32 v84, v95, v84, vcc
	v_cmp_neq_f32_e32 vcc, -1.0, v88
	v_sub_f32_e32 v100, v86, v99
	s_nop 0
	v_cndmask_b32_e32 v84, v96, v84, vcc
	v_cmp_lt_f32_e64 vcc, |v88|, s23
	s_nop 1
	v_cndmask_b32_e32 v84, v84, v88, vcc
	v_sub_f32_e32 v64, v64, v84
	v_cvt_f64_f32_e32 v[84:85], v87
	v_frexp_exp_i32_f64_e32 v84, v[84:85]
	v_frexp_mant_f32_e32 v85, v87
	v_cmp_gt_f32_e32 vcc, s21, v85
	v_mul_f32_e32 v64, 0x3fb8aa3b, v64
	global_store_dword v[68:69], v64, off offset:196
	global_store_dword v[72:73], v64, off
	v_subbrev_co_u32_e32 v84, vcc, 0, v84, vcc
	v_cvt_f32_i32_e32 v85, v84
	v_sub_u32_e32 v84, 0, v84
	v_ldexp_f32 v89, v87, v84
	v_sub_f32_e32 v87, v99, v87
	v_add_f32_e32 v87, 1.0, v87
	v_add_f32_e32 v99, 1.0, v89
	v_add_f32_e32 v87, v100, v87
	v_add_f32_e32 v100, -1.0, v99
	v_ldexp_f32 v84, v87, v84
	v_sub_f32_e32 v100, v89, v100
	v_add_f32_e32 v100, v84, v100
	v_add_f32_e32 v98, -1.0, v89
	v_add_f32_e32 v101, v99, v100
	v_add_f32_e32 v87, 1.0, v98
	v_rcp_f32_e32 v102, v101
	v_sub_f32_e32 v87, v89, v87
	v_add_f32_e32 v84, v84, v87
	v_add_f32_e32 v87, v98, v84
	v_mul_f32_e32 v89, v87, v102
	v_mul_f32_e32 v103, v101, v89
	v_sub_f32_e32 v99, v101, v99
	v_sub_f32_e32 v99, v100, v99
	v_fma_f32 v100, v89, v101, -v103
	v_fmac_f32_e32 v100, v89, v99
	v_add_f32_e32 v104, v103, v100
	v_sub_f32_e32 v105, v87, v104
	v_sub_f32_e32 v98, v87, v98
	v_sub_f32_e32 v87, v87, v105
	v_sub_f32_e32 v103, v104, v103
	v_sub_f32_e32 v84, v84, v98
	v_sub_f32_e32 v87, v87, v104
	v_sub_f32_e32 v100, v103, v100
	v_add_f32_e32 v84, v84, v87
	v_add_f32_e32 v84, v100, v84
	v_add_f32_e32 v87, v105, v84
	v_mul_f32_e32 v98, v102, v87
	v_mul_f32_e32 v103, v101, v98
	v_add_f32_e32 v100, v89, v98
	v_fma_f32 v101, v98, v101, -v103
	v_sub_f32_e32 v89, v100, v89
	v_fmac_f32_e32 v101, v98, v99
	v_sub_f32_e32 v89, v98, v89
	v_add_f32_e32 v98, v103, v101
	v_sub_f32_e32 v99, v87, v98
	v_sub_f32_e32 v103, v98, v103
	v_sub_f32_e32 v101, v103, v101
	v_sub_f32_e32 v103, v105, v87
	v_sub_f32_e32 v87, v87, v99
	v_add_f32_e32 v84, v84, v103
	v_sub_f32_e32 v87, v87, v98
	v_add_f32_e32 v84, v84, v87
	v_add_f32_e32 v84, v101, v84
	v_add_f32_e32 v84, v99, v84
	v_mul_f32_e32 v84, v102, v84
	v_add_f32_e32 v84, v89, v84
	v_add_f32_e32 v87, v100, v84
	v_mul_f32_e32 v98, v87, v87
	v_fmamk_f32 v101, v98, 0x3e9b6dac, v93
	v_mul_f32_e32 v99, v87, v98
	v_fmaak_f32 v98, v98, v101, 0x3f2aaada
	v_ldexp_f32 v89, v87, 1
	v_mul_f32_e32 v98, v99, v98
	v_add_f32_e32 v99, v89, v98
	v_sub_f32_e32 v87, v87, v100
	v_min_f32_e32 v64, 0, v82
	v_mul_f32_e32 v82, 0x3f317218, v85
	v_sub_f32_e32 v84, v84, v87
	v_sub_f32_e32 v87, v99, v89
	v_fma_f32 v88, v85, s12, -v82
	v_ldexp_f32 v84, v84, 1
	v_sub_f32_e32 v87, v98, v87
	v_fmac_f32_e32 v88, 0xb102e308, v85
	v_add_f32_e32 v84, v84, v87
	v_add_f32_e32 v85, v82, v88
	v_add_f32_e32 v87, v99, v84
	v_add_f32_e32 v89, v85, v87
	v_sub_f32_e32 v82, v85, v82
	v_sub_f32_e32 v82, v88, v82
	v_sub_f32_e32 v88, v87, v99
	v_sub_f32_e32 v98, v89, v85
	v_sub_f32_e32 v84, v84, v88
	v_sub_f32_e32 v87, v87, v98
	v_sub_f32_e32 v98, v89, v98
	v_add_f32_e32 v88, v82, v84
	v_sub_f32_e32 v85, v85, v98
	v_add_f32_e32 v85, v87, v85
	v_sub_f32_e32 v98, v88, v82
	v_add_f32_e32 v85, v88, v85
	v_sub_f32_e32 v88, v88, v98
	v_add_f32_e32 v87, v89, v85
	v_sub_f32_e32 v84, v84, v98
	v_sub_f32_e32 v82, v82, v88
	v_add_f32_e32 v82, v84, v82
	v_sub_f32_e32 v84, v87, v89
	v_sub_f32_e32 v84, v85, v84
	v_add_f32_e32 v82, v82, v84
	v_add_f32_e32 v84, v83, v97
	v_mul_f32_e64 v83, |v84|, s19
	v_add_f32_e32 v82, v87, v82
	v_cmp_neq_f32_e32 vcc, s33, v86
	v_exp_f32_e32 v85, v83
	s_nop 0
	v_cndmask_b32_e32 v82, v94, v82, vcc
	v_cmp_ngt_f32_e32 vcc, -1.0, v86
; __device__ __forceinline__ void p1_side_task(int c, LAS unsigned char* lds, const bf16_t* XN, const bf16_t* WIN, const float* b_f, float* LF, bf16_t* Kb, bf16_t* Vb, bf16_t* P1b) {
;     ...
;             for (int j = 0; j < 4; ++j) { const float xx = acc[g][j] + bfh; const float v = (fminf(xx, 0.f) - log1pf(__expf(-fabsf(xx)))) * LOG2E; const int m = 4 * fq + j;
;                 if (g < 2) { const int row = 32 * c + 16 * g + m; LF[(size_t)((row >> 12) * NH + fr) * KVROWS + 64 + (row & 4095)] = v; }
;                 else if (c == 0) { LF[(size_t)fr * KVROWS + 48 + m] = v; LF[(size_t)(NH + fr) * KVROWS + 48 + m] = v; } }
	s_nop 1
	v_cndmask_b32_e32 v82, v95, v82, vcc
	v_cmp_neq_f32_e32 vcc, -1.0, v86
	s_nop 1
	v_cndmask_b32_e32 v82, v96, v82, vcc
	v_cmp_lt_f32_e64 vcc, |v86|, s23
	s_nop 1
	v_cndmask_b32_e32 v82, v82, v86, vcc
	v_add_f32_e32 v86, 1.0, v85
	v_sub_f32_e32 v64, v64, v82
	v_cvt_f64_f32_e32 v[82:83], v86
	v_frexp_exp_i32_f64_e32 v82, v[82:83]
	v_frexp_mant_f32_e32 v83, v86
	v_cmp_gt_f32_e32 vcc, s21, v83
	v_add_f32_e32 v97, -1.0, v86
	v_sub_f32_e32 v98, v85, v97
	v_subbrev_co_u32_e32 v82, vcc, 0, v82, vcc
	v_cvt_f32_i32_e32 v83, v82
	v_sub_u32_e32 v82, 0, v82
	v_ldexp_f32 v88, v86, v82
	v_sub_f32_e32 v86, v97, v86
	v_add_f32_e32 v86, 1.0, v86
	v_add_f32_e32 v97, 1.0, v88
	v_add_f32_e32 v86, v98, v86
	v_add_f32_e32 v98, -1.0, v97
	v_ldexp_f32 v82, v86, v82
	v_sub_f32_e32 v98, v88, v98
	v_add_f32_e32 v98, v82, v98
	v_add_f32_e32 v89, -1.0, v88
	v_add_f32_e32 v99, v97, v98
	v_add_f32_e32 v86, 1.0, v89
	v_rcp_f32_e32 v100, v99
	v_sub_f32_e32 v86, v88, v86
	v_add_f32_e32 v82, v82, v86
	v_add_f32_e32 v86, v89, v82
	v_mul_f32_e32 v88, v86, v100
	v_mul_f32_e32 v101, v99, v88
	v_sub_f32_e32 v97, v99, v97
	v_sub_f32_e32 v97, v98, v97
	v_fma_f32 v98, v88, v99, -v101
	v_fmac_f32_e32 v98, v88, v97
	v_add_f32_e32 v102, v101, v98
	v_sub_f32_e32 v103, v86, v102
	v_sub_f32_e32 v89, v86, v89
	v_sub_f32_e32 v86, v86, v103
	v_sub_f32_e32 v101, v102, v101
	v_sub_f32_e32 v82, v82, v89
	v_sub_f32_e32 v86, v86, v102
	v_sub_f32_e32 v98, v101, v98
	v_add_f32_e32 v82, v82, v86
	v_add_f32_e32 v82, v98, v82
	v_add_f32_e32 v86, v103, v82
	v_mul_f32_e32 v89, v100, v86
	v_mul_f32_e32 v101, v99, v89
	v_add_f32_e32 v98, v88, v89
	v_fma_f32 v99, v89, v99, -v101
	v_sub_f32_e32 v88, v98, v88
	v_fmac_f32_e32 v99, v89, v97
	v_sub_f32_e32 v88, v89, v88
	v_add_f32_e32 v89, v101, v99
	v_sub_f32_e32 v97, v86, v89
	v_sub_f32_e32 v101, v89, v101
	v_sub_f32_e32 v99, v101, v99
	v_sub_f32_e32 v101, v103, v86
	v_sub_f32_e32 v86, v86, v97
	v_add_f32_e32 v82, v82, v101
	v_sub_f32_e32 v86, v86, v89
	v_add_f32_e32 v82, v82, v86
	v_add_f32_e32 v82, v99, v82
	v_add_f32_e32 v82, v97, v82
	v_mul_f32_e32 v82, v100, v82
	v_add_f32_e32 v82, v88, v82
	v_add_f32_e32 v86, v98, v82
	v_mul_f32_e32 v89, v86, v86
	v_fmamk_f32 v99, v89, 0x3e9b6dac, v93
	v_mul_f32_e32 v97, v86, v89
	v_fmaak_f32 v89, v89, v99, 0x3f2aaada
	v_ldexp_f32 v88, v86, 1
	v_mul_f32_e32 v89, v97, v89
	v_mul_f32_e32 v64, 0x3fb8aa3b, v64
	v_add_f32_e32 v97, v88, v89
	v_sub_f32_e32 v86, v86, v98
	global_store_dword v[68:69], v64, off offset:200
	global_store_dword v[74:75], v64, off
	v_min_f32_e32 v64, 0, v84
	v_mul_f32_e32 v84, 0x3f317218, v83
	v_sub_f32_e32 v82, v82, v86
	v_sub_f32_e32 v86, v97, v88
	v_fma_f32 v87, v83, s12, -v84
	v_ldexp_f32 v82, v82, 1
	v_sub_f32_e32 v86, v89, v86
	v_fmac_f32_e32 v87, 0xb102e308, v83
	v_add_f32_e32 v82, v82, v86
	v_add_f32_e32 v83, v84, v87
	v_add_f32_e32 v86, v97, v82
	v_add_f32_e32 v88, v83, v86
	v_sub_f32_e32 v84, v83, v84
	v_sub_f32_e32 v84, v87, v84
	v_sub_f32_e32 v87, v86, v97
	v_sub_f32_e32 v89, v88, v83
	v_sub_f32_e32 v82, v82, v87
	v_sub_f32_e32 v86, v86, v89
	v_sub_f32_e32 v89, v88, v89
	v_add_f32_e32 v87, v84, v82
	v_sub_f32_e32 v83, v83, v89
	v_add_f32_e32 v83, v86, v83
	v_sub_f32_e32 v89, v87, v84
	v_add_f32_e32 v83, v87, v83
	v_sub_f32_e32 v87, v87, v89
	v_add_f32_e32 v86, v88, v83
	v_sub_f32_e32 v82, v82, v89
	v_sub_f32_e32 v84, v84, v87
	v_add_f32_e32 v82, v82, v84
	v_sub_f32_e32 v84, v86, v88
	v_sub_f32_e32 v83, v83, v84
	v_add_f32_e32 v82, v82, v83
	v_add_f32_e32 v82, v86, v82
	v_cmp_neq_f32_e32 vcc, s33, v85
	s_nop 1
	v_cndmask_b32_e32 v82, v94, v82, vcc
	v_cmp_ngt_f32_e32 vcc, -1.0, v85
	s_nop 1
	v_cndmask_b32_e32 v82, v95, v82, vcc
	v_cmp_neq_f32_e32 vcc, -1.0, v85
	s_nop 1
	v_cndmask_b32_e32 v82, v96, v82, vcc
	v_cmp_lt_f32_e64 vcc, |v85|, s23
	s_nop 1
	v_cndmask_b32_e32 v82, v82, v85, vcc
	v_sub_f32_e32 v64, v64, v82
	v_mul_f32_e32 v64, 0x3fb8aa3b, v64
	global_store_dword v[68:69], v64, off offset:204
	global_store_dword v[76:77], v64, off
